# v51 plus K-loop scalar bookkeeping (pointer bumps, selects) moved from the head of the load segment into the preceding MFMA burst
# baseline (speedup 1.0000x reference)
;     __device__ __forceinline__ bool next(int i, Unit& u) const { if (!StaticOrder::next(i / 3, u)) return false; u.aux = i % 3; return true; }
; #define PG8_STAGE(bufoff, gbase, voff) do { _Pragma("unroll") for (int _i = 0; _i < 2; ++_i) \
;         __builtin_amdgcn_global_load_lds((const unsigned*)((const char*)(gbase) + (voff)[_i]), (PG8_LAS unsigned*)(lds + (bufoff) + ldsw + _i * 8192), 16, 0, 0); } while (0)
; #define PG8_LDA(dst, b, h) do { _Pragma("unroll") for (int m = 0; m < 4; ++m) _Pragma("unroll") for (int k = 0; k < 2; ++k) dst[m][k] = *(const PG8_LAS bf16x8*)(lds + PG8_SA(b, h) + aoff + m * 2048 + k * 1024); } while (0)
; #define PG8_LDB(dst, b, h) do { _Pragma("unroll") for (int n = 0; n < 2; ++n) _Pragma("unroll") for (int k = 0; k < 2; ++k) dst[n][k] = *(const PG8_LAS bf16x8*)(lds + PG8_SB(b, h) + boff + n * 2048 + k * 1024); } while (0)
; #define PG8_WAIT_V(n) asm volatile("s_waitcnt vmcnt(" #n ")" ::: "memory")
; #define PG8_WAIT_L(n) asm volatile("s_waitcnt lgkmcnt(" #n ")" ::: "memory")
; template <class Epi, class Sched, bool ALIGN_EPI = false, bool SP2 = false>
; __device__ __forceinline__ void gemm_phase(PG8_LAS unsigned char* lds, const Gemm g, const Sched& S, const Epi& E) {
;     ...
;         const bool has_next = S.next(ui + 1, nxt);
;         const char* nA = cA; const char* nB = cB; if (has_next) S.bases(g, nxt, tstep, nA, nB);
;         for (int t = 0; t < nt; t += 2) {
;             const bool last = (t == nt - 2);
;             const char* a1 = cA + (size_t)(t + 1) * kstep;
;             const char* a2 = last ? nA : cA + (size_t)(t + 2) * kstep; const char* b2 = last ? nB : cB + (size_t)(t + 2) * kstep;
;             const char* a3 = a2 + kstep; const char* b3 = b2 + kstep;
;             if (last && has_next) S.a_ready(nxt);
;             if constexpr (SP2) {
;             PG8_LDB(B0, 0, 0); PG8_LDB(B1, 0, 1); PG8_SCHED; PG8_LDA(At, 0, 0); PG8_STAGE(PG8_SA(1, 1), a1 + hstep, voffA);
;             PG8_WAIT_V(8); PG8_WAIT_L(0); PG8_BAR; PG8_MMA(0, 0, At, B0); PG8_MMA(0, 1, At, B1); PG8_BAR; PG8_SCHED;
;     ...
;         if (zero_acc) {
; #pragma unroll
;         for (int a = 0; a < 2; ++a)
; #pragma unroll
;             for (int b = 0; b < 2; ++b)
; #pragma unroll
;                 for (int m = 0; m < 4; ++m)
; #pragma unroll
;                     for (int n = 0; n < 2; ++n) acc[a][b][m][n] = (f32x4){0.f, 0.f, 0.f, 0.f};
.LBB0_300:
	s_ashr_i32 s13, s12, 31
	s_lshl_b64 s[28:29], s[12:13], 20
	s_add_u32 s28, s43, s28
	s_addc_u32 s29, s44, s29
	s_ashr_i32 s11, s10, 31
	s_lshl_b64 s[30:31], s[10:11], 20
	s_add_u32 s30, s45, s30
	s_addc_u32 s31, s46, s31
	s_and_b64 s[40:41], s[0:1], exec
	s_cselect_b32 s11, s29, s37
	s_cselect_b32 s13, s28, s36
	s_cselect_b32 s56, s31, s39
	s_cselect_b32 s57, s30, s38
	s_add_u32 s36, s36, 0x80080
	s_addc_u32 s37, s37, 0
	s_add_u32 s58, s38, 0x100
	v_mov_b32_e32 v4, 0
	s_addc_u32 s59, s39, 0
	s_mov_b32 s60, -2
	v_mov_b32_e32 v5, v4
	v_mov_b32_e32 v6, v4
	v_mov_b32_e32 v7, v4
	v_mov_b32_e32 v12, v4
	v_mov_b32_e32 v13, v4
	v_mov_b32_e32 v14, v4
	v_mov_b32_e32 v15, v4
	v_mov_b32_e32 v20, v4
	v_mov_b32_e32 v21, v4
	v_mov_b32_e32 v22, v4
	v_mov_b32_e32 v23, v4
	v_mov_b32_e32 v28, v4
	v_mov_b32_e32 v29, v4
	v_mov_b32_e32 v30, v4
	v_mov_b32_e32 v31, v4
	v_mov_b32_e32 v36, v4
	v_mov_b32_e32 v37, v4
	v_mov_b32_e32 v38, v4
	v_mov_b32_e32 v39, v4
	v_mov_b32_e32 v44, v4
	v_mov_b32_e32 v45, v4
	v_mov_b32_e32 v46, v4
	v_mov_b32_e32 v47, v4
	v_mov_b32_e32 v52, v4
	v_mov_b32_e32 v53, v4
	v_mov_b32_e32 v54, v4
	v_mov_b32_e32 v55, v4
	v_mov_b32_e32 v60, v4
	v_mov_b32_e32 v61, v4
	v_mov_b32_e32 v62, v4
	v_mov_b32_e32 v63, v4
	v_mov_b32_e32 v8, v4
	v_mov_b32_e32 v9, v4
	v_mov_b32_e32 v10, v4
	v_mov_b32_e32 v11, v4
	v_mov_b32_e32 v16, v4
	v_mov_b32_e32 v17, v4
	v_mov_b32_e32 v18, v4
	v_mov_b32_e32 v19, v4
	v_mov_b32_e32 v24, v4
	v_mov_b32_e32 v25, v4
	v_mov_b32_e32 v26, v4
	v_mov_b32_e32 v27, v4
	v_mov_b32_e32 v32, v4
	v_mov_b32_e32 v33, v4
	v_mov_b32_e32 v34, v4
	v_mov_b32_e32 v35, v4
	v_mov_b32_e32 v40, v4
	v_mov_b32_e32 v41, v4
	v_mov_b32_e32 v42, v4
	v_mov_b32_e32 v43, v4
	v_mov_b32_e32 v48, v4
	v_mov_b32_e32 v49, v4
	v_mov_b32_e32 v50, v4
	v_mov_b32_e32 v51, v4
	v_mov_b32_e32 v56, v4
	v_mov_b32_e32 v57, v4
	v_mov_b32_e32 v58, v4
	v_mov_b32_e32 v59, v4
	v_mov_b32_e32 v64, v4
	v_mov_b32_e32 v65, v4
	v_mov_b32_e32 v66, v4
	v_mov_b32_e32 v67, v4
	v_mov_b32_e32 v68, v4
	v_mov_b32_e32 v69, v4
	v_mov_b32_e32 v70, v4
	v_mov_b32_e32 v71, v4
	v_mov_b32_e32 v76, v4
	v_mov_b32_e32 v77, v4
	v_mov_b32_e32 v78, v4
	v_mov_b32_e32 v79, v4
	v_mov_b32_e32 v84, v4
	v_mov_b32_e32 v85, v4
	v_mov_b32_e32 v86, v4
	v_mov_b32_e32 v87, v4
	v_mov_b32_e32 v92, v4
	v_mov_b32_e32 v93, v4
	v_mov_b32_e32 v94, v4
	v_mov_b32_e32 v95, v4
	v_mov_b32_e32 v100, v4
	v_mov_b32_e32 v101, v4
	v_mov_b32_e32 v102, v4
	v_mov_b32_e32 v103, v4
	v_mov_b32_e32 v108, v4
	v_mov_b32_e32 v109, v4
	v_mov_b32_e32 v110, v4
	v_mov_b32_e32 v111, v4
	v_mov_b32_e32 v116, v4
	v_mov_b32_e32 v117, v4
	v_mov_b32_e32 v118, v4
	v_mov_b32_e32 v119, v4
	v_mov_b32_e32 v124, v4
	v_mov_b32_e32 v125, v4
	v_mov_b32_e32 v126, v4
	v_mov_b32_e32 v127, v4
	v_mov_b32_e32 v72, v4
	v_mov_b32_e32 v73, v4
	v_mov_b32_e32 v74, v4
	v_mov_b32_e32 v75, v4
	v_mov_b32_e32 v80, v4
	v_mov_b32_e32 v81, v4
	v_mov_b32_e32 v82, v4
	v_mov_b32_e32 v83, v4
	v_mov_b32_e32 v88, v4
	v_mov_b32_e32 v89, v4
	v_mov_b32_e32 v90, v4
	v_mov_b32_e32 v91, v4
	v_mov_b32_e32 v96, v4
	v_mov_b32_e32 v97, v4
	v_mov_b32_e32 v98, v4
	v_mov_b32_e32 v99, v4
	v_mov_b32_e32 v104, v4
	v_mov_b32_e32 v105, v4
	v_mov_b32_e32 v106, v4
	v_mov_b32_e32 v107, v4
	v_mov_b32_e32 v112, v4
	v_mov_b32_e32 v113, v4
	v_mov_b32_e32 v114, v4
	v_mov_b32_e32 v115, v4
	v_mov_b32_e32 v120, v4
	v_mov_b32_e32 v121, v4
	v_mov_b32_e32 v122, v4
	v_mov_b32_e32 v123, v4
	v_mov_b32_e32 v128, v4
	v_mov_b32_e32 v129, v4
	v_mov_b32_e32 v130, v4
	v_mov_b32_e32 v131, v4
	v_add_u32_e32 v249, 0x10000, v150
	ds_read_b128 v[142:145], v249
	ds_read_b128 v[146:149], v249 offset:1024
	ds_read_b128 v[154:157], v249 offset:2048
	ds_read_b128 v[158:161], v249 offset:3072
	s_add_u32 s38, s36, 0xfff80080
	s_addc_u32 s39, s37, -1
	s_add_i32 s61, 0, 0x10000
	s_cmp_eq_u32 s60, 28
	s_cselect_b32 s41, s11, s39
	s_cselect_b32 s40, s13, s38
	s_cselect_b32 s39, s56, s59
	s_cselect_b32 s38, s57, s58
	s_add_i32 s64, 0, 0x14000
	.p2align 6
	s_nop 0
.LBB0_301:
	ds_read_b128 v[174:177], v249 offset:16384
	ds_read_b128 v[178:181], v249 offset:17408
	ds_read_b128 v[204:207], v249 offset:18432
	ds_read_b128 v[208:211], v249 offset:19456
	s_add_i32 m0, s47, 0xc000
	ds_read_b128 v[212:215], v153
	ds_read_b128 v[216:219], v153 offset:1024
	ds_read_b128 v[220:223], v153 offset:2048
	ds_read_b128 v[224:227], v153 offset:3072
	ds_read_b128 v[228:231], v153 offset:4096
	ds_read_b128 v[232:235], v153 offset:5120
	ds_read_b128 v[236:239], v153 offset:6144
	ds_read_b128 v[240:243], v153 offset:7168
	global_load_lds_dwordx4 v138, s[36:37]
	s_add_i32 m0, s47, 0xe000
	s_nop 0
	global_load_lds_dwordx4 v140, s[36:37]
	s_nop 0
	s_waitcnt vmcnt(8) lgkmcnt(0)
	s_barrier
; #define PG8_STAGE(bufoff, gbase, voff) do { _Pragma("unroll") for (int _i = 0; _i < 2; ++_i) \
;         __builtin_amdgcn_global_load_lds((const unsigned*)((const char*)(gbase) + (voff)[_i]), (PG8_LAS unsigned*)(lds + (bufoff) + ldsw + _i * 8192), 16, 0, 0); } while (0)
; #define PG8_LDA(dst, b, h) do { _Pragma("unroll") for (int m = 0; m < 4; ++m) _Pragma("unroll") for (int k = 0; k < 2; ++k) dst[m][k] = *(const PG8_LAS bf16x8*)(lds + PG8_SA(b, h) + aoff + m * 2048 + k * 1024); } while (0)
; #define PG8_LDB(dst, b, h) do { _Pragma("unroll") for (int n = 0; n < 2; ++n) _Pragma("unroll") for (int k = 0; k < 2; ++k) dst[n][k] = *(const PG8_LAS bf16x8*)(lds + PG8_SB(b, h) + boff + n * 2048 + k * 1024); } while (0)
; #define PG8_MMA(ai, bj, At, Bt) do { __builtin_amdgcn_s_setprio(1); _Pragma("unroll") for (int m = 0; m < 4; ++m) _Pragma("unroll") for (int n = 0; n < 2; ++n) _Pragma("unroll") for (int k = 0; k < 2; ++k) \
;         acc[ai][bj][m][n] = __builtin_amdgcn_mfma_f32_16x16x32_bf16(Bt[n][k], At[m][k], acc[ai][bj][m][n], 0, 0, 0); __builtin_amdgcn_s_setprio(0); } while (0)
; #define PG8_WAIT_V(n) asm volatile("s_waitcnt vmcnt(" #n ")" ::: "memory")
; #define PG8_WAIT_L(n) asm volatile("s_waitcnt lgkmcnt(" #n ")" ::: "memory")
; #define PG8_BAR __builtin_amdgcn_s_barrier()
; #define PG8_SCHED __builtin_amdgcn_sched_barrier(0)
; template <class Epi, class Sched, bool ALIGN_EPI = false, bool SP2 = false>
; __device__ __forceinline__ void gemm_phase(PG8_LAS unsigned char* lds, const Gemm g, const Sched& S, const Epi& E) {
;     ...
;             PG8_WAIT_V(8); PG8_WAIT_L(0); PG8_BAR; PG8_MMA(0, 0, At, B0); PG8_MMA(0, 1, At, B1); PG8_BAR; PG8_SCHED;
;             PG8_LDA(At, 0, 1); PG8_STAGE(PG8_SB(0, 0), b2, voffB); PG8_STAGE(PG8_SB(0, 1), b2 + hstep, voffB); PG8_STAGE(PG8_SA(0, 0), a2, voffA);
;             PG8_WAIT_V(8); PG8_WAIT_L(0); PG8_BAR; PG8_MMA(1, 0, At, B0); PG8_MMA(1, 1, At, B1); PG8_BAR; PG8_SCHED;
;             PG8_LDB(B0, 1, 0); PG8_LDB(B1, 1, 1); PG8_SCHED; PG8_LDA(At, 1, 0); PG8_STAGE(PG8_SA(0, 1), a2 + hstep, voffA);
;             PG8_WAIT_V(8); PG8_WAIT_L(0); PG8_BAR; PG8_MMA(0, 0, At, B0); PG8_MMA(0, 1, At, B1); PG8_BAR; PG8_SCHED;
	s_setprio 0
	s_waitcnt lgkmcnt(0)
	v_mfma_f32_16x16x32_bf16 v[128:131], v[142:145], v[212:215], v[128:131]
	v_mfma_f32_16x16x32_bf16 v[120:123], v[154:157], v[212:215], v[120:123]
	v_mfma_f32_16x16x32_bf16 v[112:115], v[142:145], v[220:223], v[112:115]
	v_mfma_f32_16x16x32_bf16 v[104:107], v[154:157], v[220:223], v[104:107]
	v_mfma_f32_16x16x32_bf16 v[96:99], v[142:145], v[228:231], v[96:99]
	v_mfma_f32_16x16x32_bf16 v[88:91], v[154:157], v[228:231], v[88:91]
	v_mfma_f32_16x16x32_bf16 v[80:83], v[142:145], v[236:239], v[80:83]
	v_mfma_f32_16x16x32_bf16 v[72:75], v[154:157], v[236:239], v[72:75]
	v_mfma_f32_16x16x32_bf16 v[128:131], v[146:149], v[216:219], v[128:131]
	v_mfma_f32_16x16x32_bf16 v[120:123], v[158:161], v[216:219], v[120:123]
	v_mfma_f32_16x16x32_bf16 v[112:115], v[146:149], v[224:227], v[112:115]
	v_mfma_f32_16x16x32_bf16 v[104:107], v[158:161], v[224:227], v[104:107]
	v_mfma_f32_16x16x32_bf16 v[96:99], v[146:149], v[232:235], v[96:99]
	v_mfma_f32_16x16x32_bf16 v[88:91], v[158:161], v[232:235], v[88:91]
	v_mfma_f32_16x16x32_bf16 v[80:83], v[146:149], v[240:243], v[80:83]
	v_mfma_f32_16x16x32_bf16 v[72:75], v[158:161], v[240:243], v[72:75]
	v_mfma_f32_16x16x32_bf16 v[124:127], v[174:177], v[212:215], v[124:127]
	v_mfma_f32_16x16x32_bf16 v[116:119], v[204:207], v[212:215], v[116:119]
	v_mfma_f32_16x16x32_bf16 v[108:111], v[174:177], v[220:223], v[108:111]
	v_mfma_f32_16x16x32_bf16 v[100:103], v[204:207], v[220:223], v[100:103]
	v_mfma_f32_16x16x32_bf16 v[92:95], v[174:177], v[228:231], v[92:95]
	v_mfma_f32_16x16x32_bf16 v[84:87], v[204:207], v[228:231], v[84:87]
	v_mfma_f32_16x16x32_bf16 v[76:79], v[174:177], v[236:239], v[76:79]
	v_mfma_f32_16x16x32_bf16 v[68:71], v[204:207], v[236:239], v[68:71]
	v_mfma_f32_16x16x32_bf16 v[124:127], v[178:181], v[216:219], v[124:127]
	v_mfma_f32_16x16x32_bf16 v[116:119], v[208:211], v[216:219], v[116:119]
	v_mfma_f32_16x16x32_bf16 v[108:111], v[178:181], v[224:227], v[108:111]
	v_mfma_f32_16x16x32_bf16 v[100:103], v[208:211], v[224:227], v[100:103]
	v_mfma_f32_16x16x32_bf16 v[92:95], v[178:181], v[232:235], v[92:95]
	v_mfma_f32_16x16x32_bf16 v[84:87], v[208:211], v[232:235], v[84:87]
	v_mfma_f32_16x16x32_bf16 v[76:79], v[178:181], v[240:243], v[76:79]
	v_mfma_f32_16x16x32_bf16 v[68:71], v[208:211], v[240:243], v[68:71]
	s_setprio 3
	s_barrier
	s_add_i32 s61, s61, s42
	s_mov_b32 m0, s61
	ds_read_b128 v[212:215], v153 offset:16384
	ds_read_b128 v[216:219], v153 offset:17408
	ds_read_b128 v[220:223], v153 offset:18432
	ds_read_b128 v[224:227], v153 offset:19456
	ds_read_b128 v[228:231], v153 offset:20480
	ds_read_b128 v[232:235], v153 offset:21504
	ds_read_b128 v[236:239], v153 offset:22528
	ds_read_b128 v[240:243], v153 offset:23552
	global_load_lds_dwordx4 v2, s[38:39]
	s_add_i32 m0, s61, 0x2000
	s_add_u32 s62, s38, 0x80000
	s_addc_u32 s63, s39, 0
	s_add_i32 s61, s64, s42
	global_load_lds_dwordx4 v132, s[38:39]
	s_mov_b32 m0, s61
	s_nop 0
	global_load_lds_dwordx4 v2, s[62:63]
	s_add_i32 m0, s61, 0x2000
	s_nop 0
	global_load_lds_dwordx4 v132, s[62:63]
	s_mov_b32 m0, s47
	s_nop 0
	global_load_lds_dwordx4 v136, s[40:41]
	s_mov_b32 m0, s48
	s_nop 0
	global_load_lds_dwordx4 v134, s[40:41]
	s_nop 0
	s_waitcnt vmcnt(8) lgkmcnt(0)
	s_barrier
	s_setprio 0
	s_waitcnt lgkmcnt(0)
	v_mfma_f32_16x16x32_bf16 v[64:67], v[142:145], v[212:215], v[64:67]
	v_mfma_f32_16x16x32_bf16 v[56:59], v[154:157], v[212:215], v[56:59]
	v_mfma_f32_16x16x32_bf16 v[48:51], v[142:145], v[220:223], v[48:51]
	v_mfma_f32_16x16x32_bf16 v[40:43], v[154:157], v[220:223], v[40:43]
	v_mfma_f32_16x16x32_bf16 v[32:35], v[142:145], v[228:231], v[32:35]
	v_mfma_f32_16x16x32_bf16 v[24:27], v[154:157], v[228:231], v[24:27]
	v_mfma_f32_16x16x32_bf16 v[16:19], v[142:145], v[236:239], v[16:19]
	v_mfma_f32_16x16x32_bf16 v[8:11], v[154:157], v[236:239], v[8:11]
	v_mfma_f32_16x16x32_bf16 v[64:67], v[146:149], v[216:219], v[64:67]
	v_mfma_f32_16x16x32_bf16 v[56:59], v[158:161], v[216:219], v[56:59]
	v_mfma_f32_16x16x32_bf16 v[48:51], v[146:149], v[224:227], v[48:51]
	v_mfma_f32_16x16x32_bf16 v[40:43], v[158:161], v[224:227], v[40:43]
	v_mfma_f32_16x16x32_bf16 v[32:35], v[146:149], v[232:235], v[32:35]
	v_mfma_f32_16x16x32_bf16 v[24:27], v[158:161], v[232:235], v[24:27]
	v_mfma_f32_16x16x32_bf16 v[16:19], v[146:149], v[240:243], v[16:19]
	v_mfma_f32_16x16x32_bf16 v[8:11], v[158:161], v[240:243], v[8:11]
	v_mfma_f32_16x16x32_bf16 v[60:63], v[174:177], v[212:215], v[60:63]
	ds_read_b128 v[142:145], v249 offset:32768
	v_mfma_f32_16x16x32_bf16 v[52:55], v[204:207], v[212:215], v[52:55]
	ds_read_b128 v[146:149], v249 offset:33792
	v_mfma_f32_16x16x32_bf16 v[44:47], v[174:177], v[220:223], v[44:47]
	ds_read_b128 v[154:157], v249 offset:34816
	v_mfma_f32_16x16x32_bf16 v[36:39], v[204:207], v[220:223], v[36:39]
	ds_read_b128 v[158:161], v249 offset:35840
	v_mfma_f32_16x16x32_bf16 v[28:31], v[174:177], v[228:231], v[28:31]
	v_mfma_f32_16x16x32_bf16 v[20:23], v[204:207], v[228:231], v[20:23]
	v_mfma_f32_16x16x32_bf16 v[12:15], v[174:177], v[236:239], v[12:15]
	v_mfma_f32_16x16x32_bf16 v[4:7], v[204:207], v[236:239], v[4:7]
	v_mfma_f32_16x16x32_bf16 v[60:63], v[178:181], v[216:219], v[60:63]
	v_mfma_f32_16x16x32_bf16 v[52:55], v[208:211], v[216:219], v[52:55]
	v_mfma_f32_16x16x32_bf16 v[44:47], v[178:181], v[224:227], v[44:47]
	v_mfma_f32_16x16x32_bf16 v[36:39], v[208:211], v[224:227], v[36:39]
	v_mfma_f32_16x16x32_bf16 v[28:31], v[178:181], v[232:235], v[28:31]
	v_mfma_f32_16x16x32_bf16 v[20:23], v[208:211], v[232:235], v[20:23]
	v_mfma_f32_16x16x32_bf16 v[12:15], v[178:181], v[240:243], v[12:15]
	v_mfma_f32_16x16x32_bf16 v[4:7], v[208:211], v[240:243], v[4:7]
	s_setprio 3
	s_barrier
; #define PG8_STAGE(bufoff, gbase, voff) do { _Pragma("unroll") for (int _i = 0; _i < 2; ++_i) \
;         __builtin_amdgcn_global_load_lds((const unsigned*)((const char*)(gbase) + (voff)[_i]), (PG8_LAS unsigned*)(lds + (bufoff) + ldsw + _i * 8192), 16, 0, 0); } while (0)
; #define PG8_LDA(dst, b, h) do { _Pragma("unroll") for (int m = 0; m < 4; ++m) _Pragma("unroll") for (int k = 0; k < 2; ++k) dst[m][k] = *(const PG8_LAS bf16x8*)(lds + PG8_SA(b, h) + aoff + m * 2048 + k * 1024); } while (0)
; #define PG8_LDB(dst, b, h) do { _Pragma("unroll") for (int n = 0; n < 2; ++n) _Pragma("unroll") for (int k = 0; k < 2; ++k) dst[n][k] = *(const PG8_LAS bf16x8*)(lds + PG8_SB(b, h) + boff + n * 2048 + k * 1024); } while (0)
; #define PG8_MMA(ai, bj, At, Bt) do { __builtin_amdgcn_s_setprio(1); _Pragma("unroll") for (int m = 0; m < 4; ++m) _Pragma("unroll") for (int n = 0; n < 2; ++n) _Pragma("unroll") for (int k = 0; k < 2; ++k) \
;         acc[ai][bj][m][n] = __builtin_amdgcn_mfma_f32_16x16x32_bf16(Bt[n][k], At[m][k], acc[ai][bj][m][n], 0, 0, 0); __builtin_amdgcn_s_setprio(0); } while (0)
; #define PG8_WAIT_V(n) asm volatile("s_waitcnt vmcnt(" #n ")" ::: "memory")
; #define PG8_WAIT_L(n) asm volatile("s_waitcnt lgkmcnt(" #n ")" ::: "memory")
; #define PG8_BAR __builtin_amdgcn_s_barrier()
; #define PG8_SCHED __builtin_amdgcn_sched_barrier(0)
; template <class Epi, class Sched, bool ALIGN_EPI = false, bool SP2 = false>
; __device__ __forceinline__ void gemm_phase(PG8_LAS unsigned char* lds, const Gemm g, const Sched& S, const Epi& E) {
;     ...
;             PG8_LDB(B0, 1, 0); PG8_LDB(B1, 1, 1); PG8_SCHED; PG8_LDA(At, 1, 0); PG8_STAGE(PG8_SA(0, 1), a2 + hstep, voffA);
;             PG8_WAIT_V(8); PG8_WAIT_L(0); PG8_BAR; PG8_MMA(0, 0, At, B0); PG8_MMA(0, 1, At, B1); PG8_BAR; PG8_SCHED;
	s_add_i32 s61, 0, 0x18000
	s_add_i32 s62, 0, 0x1c000
	ds_read_b128 v[174:177], v249 offset:49152
	ds_read_b128 v[178:181], v249 offset:50176
	ds_read_b128 v[204:207], v249 offset:51200
	ds_read_b128 v[208:211], v249 offset:52224
	s_add_u32 s100, s40, 0x80
	s_addc_u32 s101, s41, 0
	s_add_u32 s40, s40, 0x80000
	s_addc_u32 s41, s41, 0
	s_mov_b32 m0, s49
	ds_read_b128 v[212:215], v153 offset:32768
	ds_read_b128 v[216:219], v153 offset:33792
	ds_read_b128 v[220:223], v153 offset:34816
	ds_read_b128 v[224:227], v153 offset:35840
	ds_read_b128 v[228:231], v153 offset:36864
	ds_read_b128 v[232:235], v153 offset:37888
	ds_read_b128 v[236:239], v153 offset:38912
	ds_read_b128 v[240:243], v153 offset:39936
	global_load_lds_dwordx4 v136, s[40:41]
	s_mov_b32 m0, s50
	s_nop 0
	global_load_lds_dwordx4 v134, s[40:41]
	s_nop 0
	s_waitcnt vmcnt(8) lgkmcnt(0)
	s_barrier
	s_setprio 0
	s_waitcnt lgkmcnt(0)
	v_mfma_f32_16x16x32_bf16 v[128:131], v[142:145], v[212:215], v[128:131]
	v_mfma_f32_16x16x32_bf16 v[120:123], v[154:157], v[212:215], v[120:123]
	v_mfma_f32_16x16x32_bf16 v[112:115], v[142:145], v[220:223], v[112:115]
	v_mfma_f32_16x16x32_bf16 v[104:107], v[154:157], v[220:223], v[104:107]
	v_mfma_f32_16x16x32_bf16 v[96:99], v[142:145], v[228:231], v[96:99]
	v_mfma_f32_16x16x32_bf16 v[88:91], v[154:157], v[228:231], v[88:91]
	v_mfma_f32_16x16x32_bf16 v[80:83], v[142:145], v[236:239], v[80:83]
	v_mfma_f32_16x16x32_bf16 v[72:75], v[154:157], v[236:239], v[72:75]
	v_mfma_f32_16x16x32_bf16 v[128:131], v[146:149], v[216:219], v[128:131]
	v_mfma_f32_16x16x32_bf16 v[120:123], v[158:161], v[216:219], v[120:123]
	v_mfma_f32_16x16x32_bf16 v[112:115], v[146:149], v[224:227], v[112:115]
	v_mfma_f32_16x16x32_bf16 v[104:107], v[158:161], v[224:227], v[104:107]
	v_mfma_f32_16x16x32_bf16 v[96:99], v[146:149], v[232:235], v[96:99]
	v_mfma_f32_16x16x32_bf16 v[88:91], v[158:161], v[232:235], v[88:91]
	v_mfma_f32_16x16x32_bf16 v[80:83], v[146:149], v[240:243], v[80:83]
	v_mfma_f32_16x16x32_bf16 v[72:75], v[158:161], v[240:243], v[72:75]
	v_mfma_f32_16x16x32_bf16 v[124:127], v[174:177], v[212:215], v[124:127]
	v_mfma_f32_16x16x32_bf16 v[116:119], v[204:207], v[212:215], v[116:119]
	v_mfma_f32_16x16x32_bf16 v[108:111], v[174:177], v[220:223], v[108:111]
	v_mfma_f32_16x16x32_bf16 v[100:103], v[204:207], v[220:223], v[100:103]
	v_mfma_f32_16x16x32_bf16 v[92:95], v[174:177], v[228:231], v[92:95]
	v_mfma_f32_16x16x32_bf16 v[84:87], v[204:207], v[228:231], v[84:87]
	v_mfma_f32_16x16x32_bf16 v[76:79], v[174:177], v[236:239], v[76:79]
	v_mfma_f32_16x16x32_bf16 v[68:71], v[204:207], v[236:239], v[68:71]
	v_mfma_f32_16x16x32_bf16 v[124:127], v[178:181], v[216:219], v[124:127]
	v_mfma_f32_16x16x32_bf16 v[116:119], v[208:211], v[216:219], v[116:119]
	v_mfma_f32_16x16x32_bf16 v[108:111], v[178:181], v[224:227], v[108:111]
	v_mfma_f32_16x16x32_bf16 v[100:103], v[208:211], v[224:227], v[100:103]
	v_mfma_f32_16x16x32_bf16 v[92:95], v[178:181], v[232:235], v[92:95]
	v_mfma_f32_16x16x32_bf16 v[84:87], v[208:211], v[232:235], v[84:87]
	v_mfma_f32_16x16x32_bf16 v[76:79], v[178:181], v[240:243], v[76:79]
	v_mfma_f32_16x16x32_bf16 v[68:71], v[208:211], v[240:243], v[68:71]
	s_setprio 3
	s_barrier
; #define PG8_STAGE(bufoff, gbase, voff) do { _Pragma("unroll") for (int _i = 0; _i < 2; ++_i) \
;         __builtin_amdgcn_global_load_lds((const unsigned*)((const char*)(gbase) + (voff)[_i]), (PG8_LAS unsigned*)(lds + (bufoff) + ldsw + _i * 8192), 16, 0, 0); } while (0)
; #define PG8_LDA(dst, b, h) do { _Pragma("unroll") for (int m = 0; m < 4; ++m) _Pragma("unroll") for (int k = 0; k < 2; ++k) dst[m][k] = *(const PG8_LAS bf16x8*)(lds + PG8_SA(b, h) + aoff + m * 2048 + k * 1024); } while (0)
; #define PG8_MMA(ai, bj, At, Bt) do { __builtin_amdgcn_s_setprio(1); _Pragma("unroll") for (int m = 0; m < 4; ++m) _Pragma("unroll") for (int n = 0; n < 2; ++n) _Pragma("unroll") for (int k = 0; k < 2; ++k) \
;         acc[ai][bj][m][n] = __builtin_amdgcn_mfma_f32_16x16x32_bf16(Bt[n][k], At[m][k], acc[ai][bj][m][n], 0, 0, 0); __builtin_amdgcn_s_setprio(0); } while (0)
; #define PG8_WAIT_V(n) asm volatile("s_waitcnt vmcnt(" #n ")" ::: "memory")
; #define PG8_WAIT_L(n) asm volatile("s_waitcnt lgkmcnt(" #n ")" ::: "memory")
; #define PG8_BAR __builtin_amdgcn_s_barrier()
; #define PG8_SCHED __builtin_amdgcn_sched_barrier(0)
; template <class Epi, class Sched, bool ALIGN_EPI = false, bool SP2 = false>
; __device__ __forceinline__ void gemm_phase(PG8_LAS unsigned char* lds, const Gemm g, const Sched& S, const Epi& E) {
;     ...
;         for (int t = 0; t < nt; t += 2) {
;             const bool last = (t == nt - 2);
;             const char* a1 = cA + (size_t)(t + 1) * kstep;
;             const char* a2 = last ? nA : cA + (size_t)(t + 2) * kstep; const char* b2 = last ? nB : cB + (size_t)(t + 2) * kstep;
;             const char* a3 = a2 + kstep; const char* b3 = b2 + kstep;
;     ...
;             PG8_LDA(At, 1, 1); PG8_STAGE(PG8_SB(1, 0), b3, voffB); PG8_STAGE(PG8_SB(1, 1), b3 + hstep, voffB); PG8_STAGE(PG8_SA(1, 0), a3, voffA);
;             PG8_WAIT_V(8); PG8_WAIT_L(0); PG8_BAR; PG8_MMA(1, 0, At, B0); PG8_MMA(1, 1, At, B1); PG8_BAR; PG8_SCHED;
	s_add_i32 s40, s61, s42
	s_add_i32 m0, s40, 0xffffff80
	ds_read_b128 v[212:215], v153 offset:49152
	ds_read_b128 v[216:219], v153 offset:50176
	ds_read_b128 v[220:223], v153 offset:51200
	ds_read_b128 v[224:227], v153 offset:52224
	ds_read_b128 v[228:231], v153 offset:53248
	ds_read_b128 v[232:235], v153 offset:54272
	ds_read_b128 v[236:239], v153 offset:55296
	ds_read_b128 v[240:243], v153 offset:56320
	global_load_lds_dwordx4 v2, s[38:39] offset:128
	s_add_i32 m0, s40, 0x1f80
	s_add_i32 s40, s62, s42
	global_load_lds_dwordx4 v132, s[38:39] offset:128
	s_add_u32 s38, s38, 0x80080
	s_addc_u32 s39, s39, 0
	s_mov_b32 m0, s40
	s_nop 0
	global_load_lds_dwordx4 v2, s[38:39]
	s_add_i32 m0, s40, 0x2000
	s_nop 0
	global_load_lds_dwordx4 v132, s[38:39]
	s_mov_b32 m0, s51
	s_nop 0
	global_load_lds_dwordx4 v136, s[100:101]
	s_mov_b32 m0, s53
	s_nop 0
	global_load_lds_dwordx4 v134, s[100:101]
	s_nop 0
	s_nop 0
	s_nop 0
	s_nop 0
	s_nop 0
	s_waitcnt vmcnt(8) lgkmcnt(0)
	s_barrier
	s_setprio 0
	s_waitcnt lgkmcnt(0)
	v_mfma_f32_16x16x32_bf16 v[64:67], v[142:145], v[212:215], v[64:67]
	v_mfma_f32_16x16x32_bf16 v[56:59], v[154:157], v[212:215], v[56:59]
	v_mfma_f32_16x16x32_bf16 v[48:51], v[142:145], v[220:223], v[48:51]
	v_mfma_f32_16x16x32_bf16 v[40:43], v[154:157], v[220:223], v[40:43]
	v_mfma_f32_16x16x32_bf16 v[32:35], v[142:145], v[228:231], v[32:35]
	v_mfma_f32_16x16x32_bf16 v[24:27], v[154:157], v[228:231], v[24:27]
	v_mfma_f32_16x16x32_bf16 v[16:19], v[142:145], v[236:239], v[16:19]
	v_mfma_f32_16x16x32_bf16 v[8:11], v[154:157], v[236:239], v[8:11]
	v_mfma_f32_16x16x32_bf16 v[64:67], v[146:149], v[216:219], v[64:67]
	v_mfma_f32_16x16x32_bf16 v[56:59], v[158:161], v[216:219], v[56:59]
	v_mfma_f32_16x16x32_bf16 v[48:51], v[146:149], v[224:227], v[48:51]
	v_mfma_f32_16x16x32_bf16 v[40:43], v[158:161], v[224:227], v[40:43]
	v_mfma_f32_16x16x32_bf16 v[32:35], v[146:149], v[232:235], v[32:35]
	v_mfma_f32_16x16x32_bf16 v[24:27], v[158:161], v[232:235], v[24:27]
	v_mfma_f32_16x16x32_bf16 v[16:19], v[146:149], v[240:243], v[16:19]
	v_mfma_f32_16x16x32_bf16 v[8:11], v[158:161], v[240:243], v[8:11]
	v_mfma_f32_16x16x32_bf16 v[60:63], v[174:177], v[212:215], v[60:63]
	ds_read_b128 v[142:145], v249
	v_mfma_f32_16x16x32_bf16 v[52:55], v[204:207], v[212:215], v[52:55]
	ds_read_b128 v[146:149], v249 offset:1024
	v_mfma_f32_16x16x32_bf16 v[44:47], v[174:177], v[220:223], v[44:47]
	ds_read_b128 v[154:157], v249 offset:2048
	v_mfma_f32_16x16x32_bf16 v[36:39], v[204:207], v[220:223], v[36:39]
	s_add_i32 s60, s60, 2
	s_add_u32 s36, s36, 0x100
	s_addc_u32 s37, s37, 0
	s_add_u32 s58, s58, 0x100
	s_addc_u32 s59, s59, 0
	s_add_u32 s38, s36, 0xfff80080
	s_addc_u32 s39, s37, -1
	s_add_i32 s61, 0, 0x10000
	s_cmp_eq_u32 s60, 28
	s_cselect_b32 s41, s11, s39
	s_cselect_b32 s40, s13, s38
	s_cselect_b32 s39, s56, s59
	s_cselect_b32 s38, s57, s58
	s_add_i32 s64, 0, 0x14000
	ds_read_b128 v[158:161], v249 offset:3072
	v_mfma_f32_16x16x32_bf16 v[28:31], v[174:177], v[228:231], v[28:31]
	v_mfma_f32_16x16x32_bf16 v[20:23], v[204:207], v[228:231], v[20:23]
	v_mfma_f32_16x16x32_bf16 v[12:15], v[174:177], v[236:239], v[12:15]
	v_mfma_f32_16x16x32_bf16 v[4:7], v[204:207], v[236:239], v[4:7]
	v_mfma_f32_16x16x32_bf16 v[60:63], v[178:181], v[216:219], v[60:63]
	v_mfma_f32_16x16x32_bf16 v[52:55], v[208:211], v[216:219], v[52:55]
	v_mfma_f32_16x16x32_bf16 v[44:47], v[178:181], v[224:227], v[44:47]
	v_mfma_f32_16x16x32_bf16 v[36:39], v[208:211], v[224:227], v[36:39]
	v_mfma_f32_16x16x32_bf16 v[28:31], v[178:181], v[232:235], v[28:31]
	v_mfma_f32_16x16x32_bf16 v[20:23], v[208:211], v[232:235], v[20:23]
	v_mfma_f32_16x16x32_bf16 v[12:15], v[178:181], v[240:243], v[12:15]
	v_mfma_f32_16x16x32_bf16 v[4:7], v[208:211], v[240:243], v[4:7]
	s_setprio 3
	s_barrier
	s_cmp_gt_u32 s60, 29
	s_cbranch_scc0 .LBB0_301
	s_and_b64 vcc, exec, s[8:9]
	s_cbranch_vccz .LBB0_304
	s_barrier

;     __device__ __forceinline__ bool next(int i, Unit& u) const { if (!StaticOrder::next(i / 3, u)) return false; u.aux = i % 3; return true; }
; #define PG8_STAGE(bufoff, gbase, voff) do { _Pragma("unroll") for (int _i = 0; _i < 2; ++_i) \
;         __builtin_amdgcn_global_load_lds((const unsigned*)((const char*)(gbase) + (voff)[_i]), (PG8_LAS unsigned*)(lds + (bufoff) + ldsw + _i * 8192), 16, 0, 0); } while (0)
; #define PG8_LDA(dst, b, h) do { _Pragma("unroll") for (int m = 0; m < 4; ++m) _Pragma("unroll") for (int k = 0; k < 2; ++k) dst[m][k] = *(const PG8_LAS bf16x8*)(lds + PG8_SA(b, h) + aoff + m * 2048 + k * 1024); } while (0)
; #define PG8_LDB(dst, b, h) do { _Pragma("unroll") for (int n = 0; n < 2; ++n) _Pragma("unroll") for (int k = 0; k < 2; ++k) dst[n][k] = *(const PG8_LAS bf16x8*)(lds + PG8_SB(b, h) + boff + n * 2048 + k * 1024); } while (0)
; #define PG8_WAIT_V(n) asm volatile("s_waitcnt vmcnt(" #n ")" ::: "memory")
; #define PG8_WAIT_L(n) asm volatile("s_waitcnt lgkmcnt(" #n ")" ::: "memory")
; template <class Epi, class Sched, bool ALIGN_EPI = false, bool SP2 = false>
; __device__ __forceinline__ void gemm_phase(PG8_LAS unsigned char* lds, const Gemm g, const Sched& S, const Epi& E) {
;     ...
;         const bool has_next = S.next(ui + 1, nxt);
;         const char* nA = cA; const char* nB = cB; if (has_next) S.bases(g, nxt, tstep, nA, nB);
;         for (int t = 0; t < nt; t += 2) {
;             const bool last = (t == nt - 2);
;             const char* a1 = cA + (size_t)(t + 1) * kstep;
;             const char* a2 = last ? nA : cA + (size_t)(t + 2) * kstep; const char* b2 = last ? nB : cB + (size_t)(t + 2) * kstep;
;             const char* a3 = a2 + kstep; const char* b3 = b2 + kstep;
;             if (last && has_next) S.a_ready(nxt);
;             if constexpr (SP2) {
;             PG8_LDB(B0, 0, 0); PG8_LDB(B1, 0, 1); PG8_SCHED; PG8_LDA(At, 0, 0); PG8_STAGE(PG8_SA(1, 1), a1 + hstep, voffA);
;             PG8_WAIT_V(8); PG8_WAIT_L(0); PG8_BAR; PG8_MMA(0, 0, At, B0); PG8_MMA(0, 1, At, B1); PG8_BAR; PG8_SCHED;
;     ...
;         if (zero_acc) {
; #pragma unroll
;         for (int a = 0; a < 2; ++a)
; #pragma unroll
;             for (int b = 0; b < 2; ++b)
; #pragma unroll
;                 for (int m = 0; m < 4; ++m)
; #pragma unroll
;                     for (int n = 0; n < 2; ++n) acc[a][b][m][n] = (f32x4){0.f, 0.f, 0.f, 0.f};
.LBB0_574:
	s_add_u32 s61, s36, 0x100
	v_mov_b32_e32 v4, 0
	s_addc_u32 s62, s37, 0
	s_mov_b32 s63, -2
	s_waitcnt lgkmcnt(0)
	v_mov_b32_e32 v5, v4
	v_mov_b32_e32 v6, v4
	v_mov_b32_e32 v7, v4
	v_mov_b32_e32 v8, v4
	v_mov_b32_e32 v9, v4
	v_mov_b32_e32 v10, v4
	v_mov_b32_e32 v11, v4
	v_mov_b32_e32 v20, v4
	v_mov_b32_e32 v21, v4
	s_waitcnt vmcnt(0)
	v_mov_b32_e32 v22, v4
	v_mov_b32_e32 v23, v4
	v_mov_b32_e32 v24, v4
	v_mov_b32_e32 v25, v4
	v_mov_b32_e32 v26, v4
	v_mov_b32_e32 v27, v4
	v_mov_b32_e32 v36, v4
	v_mov_b32_e32 v37, v4
	v_mov_b32_e32 v38, v4
	v_mov_b32_e32 v39, v4
	v_mov_b32_e32 v40, v4
	v_mov_b32_e32 v41, v4
	v_mov_b32_e32 v42, v4
	v_mov_b32_e32 v43, v4
	v_mov_b32_e32 v52, v4
	v_mov_b32_e32 v53, v4
	v_mov_b32_e32 v54, v4
	v_mov_b32_e32 v55, v4
	v_mov_b32_e32 v56, v4
	v_mov_b32_e32 v57, v4
	v_mov_b32_e32 v58, v4
	v_mov_b32_e32 v59, v4
	v_mov_b32_e32 v12, v4
	v_mov_b32_e32 v13, v4
	v_mov_b32_e32 v14, v4
	v_mov_b32_e32 v15, v4
	v_mov_b32_e32 v16, v4
	v_mov_b32_e32 v17, v4
	v_mov_b32_e32 v18, v4
	v_mov_b32_e32 v19, v4
	v_mov_b32_e32 v28, v4
	v_mov_b32_e32 v29, v4
	v_mov_b32_e32 v30, v4
	v_mov_b32_e32 v31, v4
	v_mov_b32_e32 v32, v4
	v_mov_b32_e32 v33, v4
	v_mov_b32_e32 v34, v4
	v_mov_b32_e32 v35, v4
	v_mov_b32_e32 v44, v4
	v_mov_b32_e32 v45, v4
	v_mov_b32_e32 v46, v4
	v_mov_b32_e32 v47, v4
	v_mov_b32_e32 v48, v4
	v_mov_b32_e32 v49, v4
	v_mov_b32_e32 v50, v4
	v_mov_b32_e32 v51, v4
	v_mov_b32_e32 v60, v4
	v_mov_b32_e32 v61, v4
	v_mov_b32_e32 v62, v4
	v_mov_b32_e32 v63, v4
	v_mov_b32_e32 v64, v4
	v_mov_b32_e32 v65, v4
	v_mov_b32_e32 v66, v4
	v_mov_b32_e32 v67, v4
	v_mov_b32_e32 v68, v4
	v_mov_b32_e32 v69, v4
	v_mov_b32_e32 v70, v4
	v_mov_b32_e32 v71, v4
	v_mov_b32_e32 v72, v4
	v_mov_b32_e32 v73, v4
	v_mov_b32_e32 v74, v4
	v_mov_b32_e32 v75, v4
	v_mov_b32_e32 v84, v4
	v_mov_b32_e32 v85, v4
	v_mov_b32_e32 v86, v4
	v_mov_b32_e32 v87, v4
	v_mov_b32_e32 v88, v4
	v_mov_b32_e32 v89, v4
	v_mov_b32_e32 v90, v4
	v_mov_b32_e32 v91, v4
	v_mov_b32_e32 v100, v4
	v_mov_b32_e32 v101, v4
	v_mov_b32_e32 v102, v4
	v_mov_b32_e32 v103, v4
	v_mov_b32_e32 v104, v4
	v_mov_b32_e32 v105, v4
	v_mov_b32_e32 v106, v4
	v_mov_b32_e32 v107, v4
	v_mov_b32_e32 v116, v4
	v_mov_b32_e32 v117, v4
	v_mov_b32_e32 v118, v4
	v_mov_b32_e32 v119, v4
	v_mov_b32_e32 v120, v4
	v_mov_b32_e32 v121, v4
	v_mov_b32_e32 v122, v4
	v_mov_b32_e32 v123, v4
	v_mov_b32_e32 v76, v4
	v_mov_b32_e32 v77, v4
	v_mov_b32_e32 v78, v4
	v_mov_b32_e32 v79, v4
	v_mov_b32_e32 v80, v4
	v_mov_b32_e32 v81, v4
	v_mov_b32_e32 v82, v4
	v_mov_b32_e32 v83, v4
	v_mov_b32_e32 v92, v4
	v_mov_b32_e32 v93, v4
	v_mov_b32_e32 v94, v4
	v_mov_b32_e32 v95, v4
	v_mov_b32_e32 v96, v4
	v_mov_b32_e32 v97, v4
	v_mov_b32_e32 v98, v4
	v_mov_b32_e32 v99, v4
	v_mov_b32_e32 v108, v4
	v_mov_b32_e32 v109, v4
	v_mov_b32_e32 v110, v4
	v_mov_b32_e32 v111, v4
	v_mov_b32_e32 v112, v4
	v_mov_b32_e32 v113, v4
	v_mov_b32_e32 v114, v4
	v_mov_b32_e32 v115, v4
	v_mov_b32_e32 v124, v4
	v_mov_b32_e32 v125, v4
	v_mov_b32_e32 v126, v4
	v_mov_b32_e32 v127, v4
	v_mov_b32_e32 v128, v4
	v_mov_b32_e32 v129, v4
	v_mov_b32_e32 v130, v4
	v_mov_b32_e32 v131, v4
	v_add_u32_e32 v247, 0x10000, v173
	ds_read_b128 v[142:145], v247
	ds_read_b128 v[146:149], v247 offset:1024
	ds_read_b128 v[150:153], v247 offset:2048
	ds_read_b128 v[154:157], v247 offset:3072
	s_add_u32 s36, s34, 0x100
	s_addc_u32 s37, s35, 0
	s_add_i32 s64, 0, 0x10000
	s_cmpk_eq_i32 s63, 0x52
	s_cselect_b32 s41, s5, s37
	s_cselect_b32 s40, s4, s36
	s_cselect_b32 s39, s31, s62
	s_cselect_b32 s38, s30, s61
	s_add_i32 s65, 0, 0x14000
	.p2align 6
	s_nop 0
.LBB0_575:
	ds_read_b128 v[158:161], v247 offset:16384
	ds_read_b128 v[174:177], v247 offset:17408
	ds_read_b128 v[180:183], v247 offset:18432
	ds_read_b128 v[204:207], v247 offset:19456
	v_lshl_add_u64 v[162:163], s[34:35], 0, v[138:139]
	s_add_i32 m0, s47, 0xc000
	ds_read_b128 v[208:211], v179
	ds_read_b128 v[212:215], v179 offset:1024
	ds_read_b128 v[216:219], v179 offset:2048
	ds_read_b128 v[220:223], v179 offset:3072
	ds_read_b128 v[224:227], v179 offset:4096
	ds_read_b128 v[228:231], v179 offset:5120
	ds_read_b128 v[232:235], v179 offset:6144
	ds_read_b128 v[236:239], v179 offset:7168
	global_load_lds_dwordx4 v[162:163], off
	v_lshl_add_u64 v[162:163], s[34:35], 0, v[140:141]
	s_add_i32 m0, s47, 0xe000
	s_nop 0
	global_load_lds_dwordx4 v[162:163], off
	s_nop 0
	s_waitcnt vmcnt(8) lgkmcnt(0)
	s_barrier
	s_setprio 0
	s_waitcnt lgkmcnt(0)
	v_mfma_f32_16x16x32_bf16 v[128:131], v[142:145], v[208:211], v[128:131]
	v_mfma_f32_16x16x32_bf16 v[124:127], v[150:153], v[208:211], v[124:127]
	v_mfma_f32_16x16x32_bf16 v[112:115], v[142:145], v[216:219], v[112:115]
	v_mfma_f32_16x16x32_bf16 v[108:111], v[150:153], v[216:219], v[108:111]
	v_mfma_f32_16x16x32_bf16 v[96:99], v[142:145], v[224:227], v[96:99]
	v_mfma_f32_16x16x32_bf16 v[92:95], v[150:153], v[224:227], v[92:95]
	v_mfma_f32_16x16x32_bf16 v[80:83], v[142:145], v[232:235], v[80:83]
	v_mfma_f32_16x16x32_bf16 v[76:79], v[150:153], v[232:235], v[76:79]
	v_mfma_f32_16x16x32_bf16 v[128:131], v[146:149], v[212:215], v[128:131]
	v_mfma_f32_16x16x32_bf16 v[124:127], v[154:157], v[212:215], v[124:127]
	v_mfma_f32_16x16x32_bf16 v[112:115], v[146:149], v[220:223], v[112:115]
	v_mfma_f32_16x16x32_bf16 v[108:111], v[154:157], v[220:223], v[108:111]
	v_mfma_f32_16x16x32_bf16 v[96:99], v[146:149], v[228:231], v[96:99]
	v_mfma_f32_16x16x32_bf16 v[92:95], v[154:157], v[228:231], v[92:95]
	v_mfma_f32_16x16x32_bf16 v[80:83], v[146:149], v[236:239], v[80:83]
	v_mfma_f32_16x16x32_bf16 v[76:79], v[154:157], v[236:239], v[76:79]
	v_mfma_f32_16x16x32_bf16 v[120:123], v[158:161], v[208:211], v[120:123]
	v_mfma_f32_16x16x32_bf16 v[116:119], v[180:183], v[208:211], v[116:119]
	v_mfma_f32_16x16x32_bf16 v[104:107], v[158:161], v[216:219], v[104:107]
	v_mfma_f32_16x16x32_bf16 v[100:103], v[180:183], v[216:219], v[100:103]
	v_mfma_f32_16x16x32_bf16 v[88:91], v[158:161], v[224:227], v[88:91]
	v_mfma_f32_16x16x32_bf16 v[84:87], v[180:183], v[224:227], v[84:87]
	v_mfma_f32_16x16x32_bf16 v[72:75], v[158:161], v[232:235], v[72:75]
	v_mfma_f32_16x16x32_bf16 v[68:71], v[180:183], v[232:235], v[68:71]
	v_mfma_f32_16x16x32_bf16 v[120:123], v[174:177], v[212:215], v[120:123]
	v_mfma_f32_16x16x32_bf16 v[116:119], v[204:207], v[212:215], v[116:119]
	v_mfma_f32_16x16x32_bf16 v[104:107], v[174:177], v[220:223], v[104:107]
	v_mfma_f32_16x16x32_bf16 v[100:103], v[204:207], v[220:223], v[100:103]
	v_mfma_f32_16x16x32_bf16 v[88:91], v[174:177], v[228:231], v[88:91]
	v_mfma_f32_16x16x32_bf16 v[84:87], v[204:207], v[228:231], v[84:87]
	v_mfma_f32_16x16x32_bf16 v[72:75], v[174:177], v[236:239], v[72:75]
	v_mfma_f32_16x16x32_bf16 v[68:71], v[204:207], v[236:239], v[68:71]
	s_setprio 3
	s_barrier
; #define PG8_STAGE(bufoff, gbase, voff) do { _Pragma("unroll") for (int _i = 0; _i < 2; ++_i) \
;         __builtin_amdgcn_global_load_lds((const unsigned*)((const char*)(gbase) + (voff)[_i]), (PG8_LAS unsigned*)(lds + (bufoff) + ldsw + _i * 8192), 16, 0, 0); } while (0)
; #define PG8_LDA(dst, b, h) do { _Pragma("unroll") for (int m = 0; m < 4; ++m) _Pragma("unroll") for (int k = 0; k < 2; ++k) dst[m][k] = *(const PG8_LAS bf16x8*)(lds + PG8_SA(b, h) + aoff + m * 2048 + k * 1024); } while (0)
; #define PG8_LDB(dst, b, h) do { _Pragma("unroll") for (int n = 0; n < 2; ++n) _Pragma("unroll") for (int k = 0; k < 2; ++k) dst[n][k] = *(const PG8_LAS bf16x8*)(lds + PG8_SB(b, h) + boff + n * 2048 + k * 1024); } while (0)
; #define PG8_MMA(ai, bj, At, Bt) do { __builtin_amdgcn_s_setprio(1); _Pragma("unroll") for (int m = 0; m < 4; ++m) _Pragma("unroll") for (int n = 0; n < 2; ++n) _Pragma("unroll") for (int k = 0; k < 2; ++k) \
;         acc[ai][bj][m][n] = __builtin_amdgcn_mfma_f32_16x16x32_bf16(Bt[n][k], At[m][k], acc[ai][bj][m][n], 0, 0, 0); __builtin_amdgcn_s_setprio(0); } while (0)
; #define PG8_WAIT_V(n) asm volatile("s_waitcnt vmcnt(" #n ")" ::: "memory")
; #define PG8_WAIT_L(n) asm volatile("s_waitcnt lgkmcnt(" #n ")" ::: "memory")
; #define PG8_BAR __builtin_amdgcn_s_barrier()
; #define PG8_SCHED __builtin_amdgcn_sched_barrier(0)
; template <class Epi, class Sched, bool ALIGN_EPI = false, bool SP2 = false>
; __device__ __forceinline__ void gemm_phase(PG8_LAS unsigned char* lds, const Gemm g, const Sched& S, const Epi& E) {
;     ...
;             PG8_LDA(At, 0, 1); PG8_STAGE(PG8_SB(0, 0), b2, voffB); PG8_STAGE(PG8_SB(0, 1), b2 + hstep, voffB); PG8_STAGE(PG8_SA(0, 0), a2, voffA);
;             PG8_WAIT_V(8); PG8_WAIT_L(0); PG8_BAR; PG8_MMA(1, 0, At, B0); PG8_MMA(1, 1, At, B1); PG8_BAR; PG8_SCHED;
;             PG8_LDB(B0, 1, 0); PG8_LDB(B1, 1, 1); PG8_SCHED; PG8_LDA(At, 1, 0); PG8_STAGE(PG8_SA(0, 1), a2 + hstep, voffA);
	s_add_i32 s34, s64, s46
	s_mov_b32 m0, s34
	ds_read_b128 v[208:211], v179 offset:16384
	ds_read_b128 v[212:215], v179 offset:17408
	ds_read_b128 v[216:219], v179 offset:18432
	ds_read_b128 v[220:223], v179 offset:19456
	ds_read_b128 v[224:227], v179 offset:20480
	ds_read_b128 v[228:231], v179 offset:21504
	ds_read_b128 v[232:235], v179 offset:22528
	ds_read_b128 v[236:239], v179 offset:23552
	global_load_lds_dwordx4 v2, s[38:39]
	s_add_i32 m0, s34, 0x2000
	s_add_u32 s34, s38, 0x158000
	s_addc_u32 s35, s39, 0
	s_add_i32 s64, s65, s46
	global_load_lds_dwordx4 v132, s[38:39]
	s_mov_b32 m0, s64
	s_nop 0
	global_load_lds_dwordx4 v2, s[34:35]
	s_add_i32 m0, s64, 0x2000
	s_nop 0
	global_load_lds_dwordx4 v132, s[34:35]
	s_mov_b32 m0, s47
	s_nop 0
	global_load_lds_dwordx4 v2, s[40:41]
	s_mov_b32 m0, s48
	s_nop 0
	global_load_lds_dwordx4 v132, s[40:41]
	s_nop 0
	s_waitcnt vmcnt(8) lgkmcnt(0)
	s_barrier
	s_setprio 0
	s_waitcnt lgkmcnt(0)
	v_mfma_f32_16x16x32_bf16 v[64:67], v[142:145], v[208:211], v[64:67]
	v_mfma_f32_16x16x32_bf16 v[60:63], v[150:153], v[208:211], v[60:63]
	v_mfma_f32_16x16x32_bf16 v[48:51], v[142:145], v[216:219], v[48:51]
	v_mfma_f32_16x16x32_bf16 v[44:47], v[150:153], v[216:219], v[44:47]
	v_mfma_f32_16x16x32_bf16 v[32:35], v[142:145], v[224:227], v[32:35]
	v_mfma_f32_16x16x32_bf16 v[28:31], v[150:153], v[224:227], v[28:31]
	v_mfma_f32_16x16x32_bf16 v[16:19], v[142:145], v[232:235], v[16:19]
	v_mfma_f32_16x16x32_bf16 v[12:15], v[150:153], v[232:235], v[12:15]
	v_mfma_f32_16x16x32_bf16 v[64:67], v[146:149], v[212:215], v[64:67]
	v_mfma_f32_16x16x32_bf16 v[60:63], v[154:157], v[212:215], v[60:63]
	v_mfma_f32_16x16x32_bf16 v[48:51], v[146:149], v[220:223], v[48:51]
	v_mfma_f32_16x16x32_bf16 v[44:47], v[154:157], v[220:223], v[44:47]
	v_mfma_f32_16x16x32_bf16 v[32:35], v[146:149], v[228:231], v[32:35]
	v_mfma_f32_16x16x32_bf16 v[28:31], v[154:157], v[228:231], v[28:31]
	v_mfma_f32_16x16x32_bf16 v[16:19], v[146:149], v[236:239], v[16:19]
	v_mfma_f32_16x16x32_bf16 v[12:15], v[154:157], v[236:239], v[12:15]
	v_mfma_f32_16x16x32_bf16 v[56:59], v[158:161], v[208:211], v[56:59]
	ds_read_b128 v[142:145], v247 offset:32768
	v_mfma_f32_16x16x32_bf16 v[52:55], v[180:183], v[208:211], v[52:55]
	ds_read_b128 v[146:149], v247 offset:33792
	v_mfma_f32_16x16x32_bf16 v[40:43], v[158:161], v[216:219], v[40:43]
	ds_read_b128 v[150:153], v247 offset:34816
	v_mfma_f32_16x16x32_bf16 v[36:39], v[180:183], v[216:219], v[36:39]
	ds_read_b128 v[154:157], v247 offset:35840
	v_mfma_f32_16x16x32_bf16 v[24:27], v[158:161], v[224:227], v[24:27]
	v_mfma_f32_16x16x32_bf16 v[20:23], v[180:183], v[224:227], v[20:23]
	v_mfma_f32_16x16x32_bf16 v[8:11], v[158:161], v[232:235], v[8:11]
	v_mfma_f32_16x16x32_bf16 v[4:7], v[180:183], v[232:235], v[4:7]
	v_mfma_f32_16x16x32_bf16 v[56:59], v[174:177], v[212:215], v[56:59]
	v_mfma_f32_16x16x32_bf16 v[52:55], v[204:207], v[212:215], v[52:55]
	v_mfma_f32_16x16x32_bf16 v[40:43], v[174:177], v[220:223], v[40:43]
	v_mfma_f32_16x16x32_bf16 v[36:39], v[204:207], v[220:223], v[36:39]
	v_mfma_f32_16x16x32_bf16 v[24:27], v[174:177], v[228:231], v[24:27]
	v_mfma_f32_16x16x32_bf16 v[20:23], v[204:207], v[228:231], v[20:23]
	v_mfma_f32_16x16x32_bf16 v[8:11], v[174:177], v[236:239], v[8:11]
	v_mfma_f32_16x16x32_bf16 v[4:7], v[204:207], v[236:239], v[4:7]
	s_setprio 3
	s_barrier
	s_add_i32 s64, 0, 0x18000
	s_add_i32 s65, 0, 0x1c000
	ds_read_b128 v[158:161], v247 offset:49152
	ds_read_b128 v[174:177], v247 offset:50176
	ds_read_b128 v[180:183], v247 offset:51200
	ds_read_b128 v[204:207], v247 offset:52224
	s_add_u32 s34, s40, 0x158000
	s_addc_u32 s35, s41, 0
	s_mov_b32 m0, s49
	ds_read_b128 v[208:211], v179 offset:32768
	ds_read_b128 v[212:215], v179 offset:33792
	ds_read_b128 v[216:219], v179 offset:34816
	ds_read_b128 v[220:223], v179 offset:35840
	ds_read_b128 v[224:227], v179 offset:36864
	ds_read_b128 v[228:231], v179 offset:37888
	ds_read_b128 v[232:235], v179 offset:38912
	ds_read_b128 v[236:239], v179 offset:39936
	global_load_lds_dwordx4 v2, s[34:35]
	s_mov_b32 m0, s50
	s_nop 0
	global_load_lds_dwordx4 v132, s[34:35]
	s_waitcnt vmcnt(8) lgkmcnt(0)
	s_barrier
; #define PG8_STAGE(bufoff, gbase, voff) do { _Pragma("unroll") for (int _i = 0; _i < 2; ++_i) \
;         __builtin_amdgcn_global_load_lds((const unsigned*)((const char*)(gbase) + (voff)[_i]), (PG8_LAS unsigned*)(lds + (bufoff) + ldsw + _i * 8192), 16, 0, 0); } while (0)
; #define PG8_LDA(dst, b, h) do { _Pragma("unroll") for (int m = 0; m < 4; ++m) _Pragma("unroll") for (int k = 0; k < 2; ++k) dst[m][k] = *(const PG8_LAS bf16x8*)(lds + PG8_SA(b, h) + aoff + m * 2048 + k * 1024); } while (0)
; #define PG8_MMA(ai, bj, At, Bt) do { __builtin_amdgcn_s_setprio(1); _Pragma("unroll") for (int m = 0; m < 4; ++m) _Pragma("unroll") for (int n = 0; n < 2; ++n) _Pragma("unroll") for (int k = 0; k < 2; ++k) \
;         acc[ai][bj][m][n] = __builtin_amdgcn_mfma_f32_16x16x32_bf16(Bt[n][k], At[m][k], acc[ai][bj][m][n], 0, 0, 0); __builtin_amdgcn_s_setprio(0); } while (0)
; #define PG8_WAIT_V(n) asm volatile("s_waitcnt vmcnt(" #n ")" ::: "memory")
; #define PG8_WAIT_L(n) asm volatile("s_waitcnt lgkmcnt(" #n ")" ::: "memory")
; #define PG8_BAR __builtin_amdgcn_s_barrier()
; #define PG8_SCHED __builtin_amdgcn_sched_barrier(0)
; template <class Epi, class Sched, bool ALIGN_EPI = false, bool SP2 = false>
; __device__ __forceinline__ void gemm_phase(PG8_LAS unsigned char* lds, const Gemm g, const Sched& S, const Epi& E) {
;     ...
;         for (int t = 0; t < nt; t += 2) {
;             const bool last = (t == nt - 2);
;             const char* a1 = cA + (size_t)(t + 1) * kstep;
;             const char* a2 = last ? nA : cA + (size_t)(t + 2) * kstep; const char* b2 = last ? nB : cB + (size_t)(t + 2) * kstep;
;             const char* a3 = a2 + kstep; const char* b3 = b2 + kstep;
;     ...
;             PG8_WAIT_V(8); PG8_WAIT_L(0); PG8_BAR; PG8_MMA(0, 0, At, B0); PG8_MMA(0, 1, At, B1); PG8_BAR; PG8_SCHED;
;             PG8_LDA(At, 1, 1); PG8_STAGE(PG8_SB(1, 0), b3, voffB); PG8_STAGE(PG8_SB(1, 1), b3 + hstep, voffB); PG8_STAGE(PG8_SA(1, 0), a3, voffA);
;             PG8_WAIT_V(8); PG8_WAIT_L(0); PG8_BAR; PG8_MMA(1, 0, At, B0); PG8_MMA(1, 1, At, B1); PG8_BAR; PG8_SCHED;
	s_setprio 0
	s_waitcnt lgkmcnt(0)
	v_mfma_f32_16x16x32_bf16 v[128:131], v[142:145], v[208:211], v[128:131]
	v_mfma_f32_16x16x32_bf16 v[124:127], v[150:153], v[208:211], v[124:127]
	v_mfma_f32_16x16x32_bf16 v[112:115], v[142:145], v[216:219], v[112:115]
	v_mfma_f32_16x16x32_bf16 v[108:111], v[150:153], v[216:219], v[108:111]
	v_mfma_f32_16x16x32_bf16 v[96:99], v[142:145], v[224:227], v[96:99]
	v_mfma_f32_16x16x32_bf16 v[92:95], v[150:153], v[224:227], v[92:95]
	v_mfma_f32_16x16x32_bf16 v[80:83], v[142:145], v[232:235], v[80:83]
	v_mfma_f32_16x16x32_bf16 v[76:79], v[150:153], v[232:235], v[76:79]
	v_mfma_f32_16x16x32_bf16 v[128:131], v[146:149], v[212:215], v[128:131]
	v_mfma_f32_16x16x32_bf16 v[124:127], v[154:157], v[212:215], v[124:127]
	v_mfma_f32_16x16x32_bf16 v[112:115], v[146:149], v[220:223], v[112:115]
	v_mfma_f32_16x16x32_bf16 v[108:111], v[154:157], v[220:223], v[108:111]
	v_mfma_f32_16x16x32_bf16 v[96:99], v[146:149], v[228:231], v[96:99]
	v_mfma_f32_16x16x32_bf16 v[92:95], v[154:157], v[228:231], v[92:95]
	v_mfma_f32_16x16x32_bf16 v[80:83], v[146:149], v[236:239], v[80:83]
	v_mfma_f32_16x16x32_bf16 v[76:79], v[154:157], v[236:239], v[76:79]
	v_mfma_f32_16x16x32_bf16 v[120:123], v[158:161], v[208:211], v[120:123]
	v_mfma_f32_16x16x32_bf16 v[116:119], v[180:183], v[208:211], v[116:119]
	v_mfma_f32_16x16x32_bf16 v[104:107], v[158:161], v[216:219], v[104:107]
	v_mfma_f32_16x16x32_bf16 v[100:103], v[180:183], v[216:219], v[100:103]
	v_mfma_f32_16x16x32_bf16 v[88:91], v[158:161], v[224:227], v[88:91]
	v_mfma_f32_16x16x32_bf16 v[84:87], v[180:183], v[224:227], v[84:87]
	v_mfma_f32_16x16x32_bf16 v[72:75], v[158:161], v[232:235], v[72:75]
	v_mfma_f32_16x16x32_bf16 v[68:71], v[180:183], v[232:235], v[68:71]
	v_mfma_f32_16x16x32_bf16 v[120:123], v[174:177], v[212:215], v[120:123]
	v_mfma_f32_16x16x32_bf16 v[116:119], v[204:207], v[212:215], v[116:119]
	v_mfma_f32_16x16x32_bf16 v[104:107], v[174:177], v[220:223], v[104:107]
	v_mfma_f32_16x16x32_bf16 v[100:103], v[204:207], v[220:223], v[100:103]
	v_mfma_f32_16x16x32_bf16 v[88:91], v[174:177], v[228:231], v[88:91]
	v_mfma_f32_16x16x32_bf16 v[84:87], v[204:207], v[228:231], v[84:87]
	v_mfma_f32_16x16x32_bf16 v[72:75], v[174:177], v[236:239], v[72:75]
	v_mfma_f32_16x16x32_bf16 v[68:71], v[204:207], v[236:239], v[68:71]
	s_setprio 3
	s_barrier
	s_add_i32 s34, s64, s46
	s_add_i32 m0, s34, 0xffffff80
	ds_read_b128 v[208:211], v179 offset:49152
	ds_read_b128 v[212:215], v179 offset:50176
	ds_read_b128 v[216:219], v179 offset:51200
	ds_read_b128 v[220:223], v179 offset:52224
	ds_read_b128 v[224:227], v179 offset:53248
	ds_read_b128 v[228:231], v179 offset:54272
	ds_read_b128 v[232:235], v179 offset:55296
	ds_read_b128 v[236:239], v179 offset:56320
	global_load_lds_dwordx4 v2, s[38:39] offset:128
	s_add_i32 m0, s34, 0x1f80
	s_add_u32 s34, s38, 0x158080
	s_addc_u32 s35, s39, 0
	global_load_lds_dwordx4 v132, s[38:39] offset:128
	s_add_i32 s38, s65, s46
	s_mov_b32 m0, s38
	s_nop 0
	global_load_lds_dwordx4 v2, s[34:35]
	s_add_i32 m0, s38, 0x2000
	s_nop 0
	global_load_lds_dwordx4 v132, s[34:35]
	s_add_i32 m0, s53, 0xffffff80
	s_nop 0
	global_load_lds_dwordx4 v2, s[40:41] offset:128
	s_add_i32 m0, s54, 0xffffff80
	s_nop 0
	global_load_lds_dwordx4 v132, s[40:41] offset:128
	s_nop 0
	s_nop 0
	s_nop 0
	s_nop 0
	s_nop 0
	s_nop 0
	s_waitcnt vmcnt(8) lgkmcnt(0)
	s_barrier
	s_setprio 0
	s_waitcnt lgkmcnt(0)
	v_mfma_f32_16x16x32_bf16 v[64:67], v[142:145], v[208:211], v[64:67]
	v_mfma_f32_16x16x32_bf16 v[60:63], v[150:153], v[208:211], v[60:63]
	v_mfma_f32_16x16x32_bf16 v[48:51], v[142:145], v[216:219], v[48:51]
	v_mfma_f32_16x16x32_bf16 v[44:47], v[150:153], v[216:219], v[44:47]
	v_mfma_f32_16x16x32_bf16 v[32:35], v[142:145], v[224:227], v[32:35]
	v_mfma_f32_16x16x32_bf16 v[28:31], v[150:153], v[224:227], v[28:31]
	v_mfma_f32_16x16x32_bf16 v[16:19], v[142:145], v[232:235], v[16:19]
	v_mfma_f32_16x16x32_bf16 v[12:15], v[150:153], v[232:235], v[12:15]
	v_mfma_f32_16x16x32_bf16 v[64:67], v[146:149], v[212:215], v[64:67]
	v_mfma_f32_16x16x32_bf16 v[60:63], v[154:157], v[212:215], v[60:63]
	v_mfma_f32_16x16x32_bf16 v[48:51], v[146:149], v[220:223], v[48:51]
	v_mfma_f32_16x16x32_bf16 v[44:47], v[154:157], v[220:223], v[44:47]
	v_mfma_f32_16x16x32_bf16 v[32:35], v[146:149], v[228:231], v[32:35]
	v_mfma_f32_16x16x32_bf16 v[28:31], v[154:157], v[228:231], v[28:31]
	v_mfma_f32_16x16x32_bf16 v[16:19], v[146:149], v[236:239], v[16:19]
	v_mfma_f32_16x16x32_bf16 v[12:15], v[154:157], v[236:239], v[12:15]
	v_mfma_f32_16x16x32_bf16 v[56:59], v[158:161], v[208:211], v[56:59]
	ds_read_b128 v[142:145], v247
	v_mfma_f32_16x16x32_bf16 v[52:55], v[180:183], v[208:211], v[52:55]
	ds_read_b128 v[146:149], v247 offset:1024
	v_mfma_f32_16x16x32_bf16 v[40:43], v[158:161], v[216:219], v[40:43]
	ds_read_b128 v[150:153], v247 offset:2048
	v_mfma_f32_16x16x32_bf16 v[36:39], v[180:183], v[216:219], v[36:39]
	s_add_i32 s63, s63, 2
	s_add_u32 s61, s61, 0x100
	s_addc_u32 s62, s62, 0
	s_mov_b64 s[34:35], s[36:37]
	s_add_u32 s36, s34, 0x100
	s_addc_u32 s37, s35, 0
	s_add_i32 s64, 0, 0x10000
	s_cmpk_eq_i32 s63, 0x52
	s_cselect_b32 s41, s5, s37
	s_cselect_b32 s40, s4, s36
	s_cselect_b32 s39, s31, s62
	s_cselect_b32 s38, s30, s61
	s_add_i32 s65, 0, 0x14000
	ds_read_b128 v[154:157], v247 offset:3072
	v_mfma_f32_16x16x32_bf16 v[24:27], v[158:161], v[224:227], v[24:27]
	v_mfma_f32_16x16x32_bf16 v[20:23], v[180:183], v[224:227], v[20:23]
	v_mfma_f32_16x16x32_bf16 v[8:11], v[158:161], v[232:235], v[8:11]
	v_mfma_f32_16x16x32_bf16 v[4:7], v[180:183], v[232:235], v[4:7]
	v_mfma_f32_16x16x32_bf16 v[56:59], v[174:177], v[212:215], v[56:59]
	v_mfma_f32_16x16x32_bf16 v[52:55], v[204:207], v[212:215], v[52:55]
	v_mfma_f32_16x16x32_bf16 v[40:43], v[174:177], v[220:223], v[40:43]
	v_mfma_f32_16x16x32_bf16 v[36:39], v[204:207], v[220:223], v[36:39]
	v_mfma_f32_16x16x32_bf16 v[24:27], v[174:177], v[228:231], v[24:27]
	v_mfma_f32_16x16x32_bf16 v[20:23], v[204:207], v[228:231], v[20:23]
	v_mfma_f32_16x16x32_bf16 v[8:11], v[174:177], v[236:239], v[8:11]
	v_mfma_f32_16x16x32_bf16 v[4:7], v[204:207], v[236:239], v[4:7]
	s_setprio 3
	s_barrier
	s_cmpk_gt_u32 s63, 0x53
	s_cbranch_scc0 .LBB0_575
	s_and_b64 vcc, exec, s[28:29]
	s_cbranch_vccz .LBB0_578
	s_barrier

;     __device__ __forceinline__ bool next(int i, Unit& u) const { if (!StaticOrder::next(i / 3, u)) return false; u.aux = i % 3; return true; }
; #define PG8_STAGE(bufoff, gbase, voff) do { _Pragma("unroll") for (int _i = 0; _i < 2; ++_i) \
;         __builtin_amdgcn_global_load_lds((const unsigned*)((const char*)(gbase) + (voff)[_i]), (PG8_LAS unsigned*)(lds + (bufoff) + ldsw + _i * 8192), 16, 0, 0); } while (0)
; #define PG8_LDA(dst, b, h) do { _Pragma("unroll") for (int m = 0; m < 4; ++m) _Pragma("unroll") for (int k = 0; k < 2; ++k) dst[m][k] = *(const PG8_LAS bf16x8*)(lds + PG8_SA(b, h) + aoff + m * 2048 + k * 1024); } while (0)
; #define PG8_LDB(dst, b, h) do { _Pragma("unroll") for (int n = 0; n < 2; ++n) _Pragma("unroll") for (int k = 0; k < 2; ++k) dst[n][k] = *(const PG8_LAS bf16x8*)(lds + PG8_SB(b, h) + boff + n * 2048 + k * 1024); } while (0)
; #define PG8_WAIT_V(n) asm volatile("s_waitcnt vmcnt(" #n ")" ::: "memory")
; #define PG8_WAIT_L(n) asm volatile("s_waitcnt lgkmcnt(" #n ")" ::: "memory")
; template <class Epi, class Sched, bool ALIGN_EPI = false, bool SP2 = false>
; __device__ __forceinline__ void gemm_phase(PG8_LAS unsigned char* lds, const Gemm g, const Sched& S, const Epi& E) {
;     ...
;         const bool has_next = S.next(ui + 1, nxt);
;         const char* nA = cA; const char* nB = cB; if (has_next) S.bases(g, nxt, tstep, nA, nB);
;         for (int t = 0; t < nt; t += 2) {
;             const bool last = (t == nt - 2);
;             const char* a1 = cA + (size_t)(t + 1) * kstep;
;             const char* a2 = last ? nA : cA + (size_t)(t + 2) * kstep; const char* b2 = last ? nB : cB + (size_t)(t + 2) * kstep;
;             const char* a3 = a2 + kstep; const char* b3 = b2 + kstep;
;             if (last && has_next) S.a_ready(nxt);
;             if constexpr (SP2) {
;             PG8_LDB(B0, 0, 0); PG8_LDB(B1, 0, 1); PG8_SCHED; PG8_LDA(At, 0, 0); PG8_STAGE(PG8_SA(1, 1), a1 + hstep, voffA);
;             PG8_WAIT_V(8); PG8_WAIT_L(0); PG8_BAR; PG8_MMA(0, 0, At, B0); PG8_MMA(0, 1, At, B1); PG8_BAR; PG8_SCHED;
;     ...
;         if (zero_acc) {
; #pragma unroll
;         for (int a = 0; a < 2; ++a)
; #pragma unroll
;             for (int b = 0; b < 2; ++b)
; #pragma unroll
;                 for (int m = 0; m < 4; ++m)
; #pragma unroll
;                     for (int n = 0; n < 2; ++n) acc[a][b][m][n] = (f32x4){0.f, 0.f, 0.f, 0.f};
.LBB0_673:
	s_add_u32 s40, s40, 0x80080
	s_addc_u32 s41, s41, 0
	s_add_u32 s35, s42, 0x100
	v_mov_b32_e32 v4, 0
	s_addc_u32 s62, s43, 0
	s_mov_b32 s63, -2
	v_mov_b32_e32 v5, v4
	v_mov_b32_e32 v6, v4
	v_mov_b32_e32 v7, v4
	v_mov_b32_e32 v8, v4
	v_mov_b32_e32 v9, v4
	v_mov_b32_e32 v10, v4
	v_mov_b32_e32 v11, v4
	v_mov_b32_e32 v16, v4
	v_mov_b32_e32 v17, v4
	v_mov_b32_e32 v18, v4
	v_mov_b32_e32 v19, v4
	v_mov_b32_e32 v24, v4
	v_mov_b32_e32 v25, v4
	v_mov_b32_e32 v26, v4
	v_mov_b32_e32 v27, v4
	v_mov_b32_e32 v32, v4
	v_mov_b32_e32 v33, v4
	v_mov_b32_e32 v34, v4
	v_mov_b32_e32 v35, v4
	v_mov_b32_e32 v40, v4
	v_mov_b32_e32 v41, v4
	v_mov_b32_e32 v42, v4
	v_mov_b32_e32 v43, v4
	v_mov_b32_e32 v48, v4
	v_mov_b32_e32 v49, v4
	v_mov_b32_e32 v50, v4
	v_mov_b32_e32 v51, v4
	v_mov_b32_e32 v56, v4
	v_mov_b32_e32 v57, v4
	v_mov_b32_e32 v58, v4
	v_mov_b32_e32 v59, v4
	v_mov_b32_e32 v12, v4
	v_mov_b32_e32 v13, v4
	v_mov_b32_e32 v14, v4
	v_mov_b32_e32 v15, v4
	v_mov_b32_e32 v20, v4
	v_mov_b32_e32 v21, v4
	v_mov_b32_e32 v22, v4
	v_mov_b32_e32 v23, v4
	v_mov_b32_e32 v28, v4
	v_mov_b32_e32 v29, v4
	v_mov_b32_e32 v30, v4
	v_mov_b32_e32 v31, v4
	v_mov_b32_e32 v36, v4
	v_mov_b32_e32 v37, v4
	v_mov_b32_e32 v38, v4
	v_mov_b32_e32 v39, v4
	v_mov_b32_e32 v44, v4
	v_mov_b32_e32 v45, v4
	v_mov_b32_e32 v46, v4
	v_mov_b32_e32 v47, v4
	v_mov_b32_e32 v52, v4
	v_mov_b32_e32 v53, v4
	v_mov_b32_e32 v54, v4
	v_mov_b32_e32 v55, v4
	v_mov_b32_e32 v60, v4
	v_mov_b32_e32 v61, v4
	v_mov_b32_e32 v62, v4
	v_mov_b32_e32 v63, v4
	v_mov_b32_e32 v64, v4
	v_mov_b32_e32 v65, v4
	v_mov_b32_e32 v66, v4
	v_mov_b32_e32 v67, v4
	v_mov_b32_e32 v68, v4
	v_mov_b32_e32 v69, v4
	v_mov_b32_e32 v70, v4
	v_mov_b32_e32 v71, v4
	v_mov_b32_e32 v72, v4
	v_mov_b32_e32 v73, v4
	v_mov_b32_e32 v74, v4
	v_mov_b32_e32 v75, v4
	v_mov_b32_e32 v80, v4
	v_mov_b32_e32 v81, v4
	v_mov_b32_e32 v82, v4
	v_mov_b32_e32 v83, v4
	v_mov_b32_e32 v88, v4
	v_mov_b32_e32 v89, v4
	v_mov_b32_e32 v90, v4
	v_mov_b32_e32 v91, v4
	v_mov_b32_e32 v96, v4
	v_mov_b32_e32 v97, v4
	v_mov_b32_e32 v98, v4
	v_mov_b32_e32 v99, v4
	v_mov_b32_e32 v104, v4
	v_mov_b32_e32 v105, v4
	v_mov_b32_e32 v106, v4
	v_mov_b32_e32 v107, v4
	v_mov_b32_e32 v112, v4
	v_mov_b32_e32 v113, v4
	v_mov_b32_e32 v114, v4
	v_mov_b32_e32 v115, v4
	v_mov_b32_e32 v120, v4
	v_mov_b32_e32 v121, v4
	v_mov_b32_e32 v122, v4
	v_mov_b32_e32 v123, v4
	v_mov_b32_e32 v76, v4
	v_mov_b32_e32 v77, v4
	v_mov_b32_e32 v78, v4
	v_mov_b32_e32 v79, v4
	v_mov_b32_e32 v84, v4
	v_mov_b32_e32 v85, v4
	v_mov_b32_e32 v86, v4
	v_mov_b32_e32 v87, v4
	v_mov_b32_e32 v92, v4
	v_mov_b32_e32 v93, v4
	v_mov_b32_e32 v94, v4
	v_mov_b32_e32 v95, v4
	v_mov_b32_e32 v100, v4
	v_mov_b32_e32 v101, v4
	v_mov_b32_e32 v102, v4
	v_mov_b32_e32 v103, v4
	v_mov_b32_e32 v108, v4
	v_mov_b32_e32 v109, v4
	v_mov_b32_e32 v110, v4
	v_mov_b32_e32 v111, v4
	v_mov_b32_e32 v116, v4
	v_mov_b32_e32 v117, v4
	v_mov_b32_e32 v118, v4
	v_mov_b32_e32 v119, v4
	v_mov_b32_e32 v124, v4
	v_mov_b32_e32 v125, v4
	v_mov_b32_e32 v126, v4
	v_mov_b32_e32 v127, v4
	v_mov_b32_e32 v128, v4
	v_mov_b32_e32 v129, v4
	v_mov_b32_e32 v130, v4
	v_mov_b32_e32 v131, v4
	v_add_u32_e32 v249, 0x10000, v173
	ds_read_b128 v[132:135], v249
	ds_read_b128 v[136:139], v249 offset:1024
	ds_read_b128 v[140:143], v249 offset:2048
	ds_read_b128 v[144:147], v249 offset:3072
	s_add_u32 s42, s40, 0xfff80080
	s_addc_u32 s43, s41, -1
	s_add_i32 s64, 0, 0x10000
	s_cmp_eq_u32 s63, 28
	s_cselect_b32 s45, s5, s43
	s_cselect_b32 s44, s4, s42
	s_cselect_b32 s43, s37, s62
	s_cselect_b32 s42, s36, s35
	s_add_i32 s66, 0, 0x14000
	.p2align 6
	s_nop 0
.LBB0_674:
	ds_read_b128 v[158:161], v249 offset:16384
	ds_read_b128 v[174:177], v249 offset:17408
	ds_read_b128 v[206:209], v249 offset:18432
	ds_read_b128 v[210:213], v249 offset:19456
	s_add_i32 m0, s39, 0xc000
	ds_read_b128 v[214:217], v204
	ds_read_b128 v[218:221], v204 offset:1024
	ds_read_b128 v[222:225], v204 offset:2048
	ds_read_b128 v[226:229], v204 offset:3072
	ds_read_b128 v[230:233], v204 offset:4096
	ds_read_b128 v[234:237], v204 offset:5120
	ds_read_b128 v[238:241], v204 offset:6144
	ds_read_b128 v[242:245], v204 offset:7168
	global_load_lds_dwordx4 v154, s[40:41]
	s_add_i32 m0, s39, 0xe000
	s_nop 0
	global_load_lds_dwordx4 v156, s[40:41]
	s_nop 0
	s_waitcnt vmcnt(8) lgkmcnt(0)
	s_barrier
	s_setprio 0
	s_waitcnt lgkmcnt(0)
	v_mfma_f32_16x16x32_bf16 v[128:131], v[132:135], v[214:217], v[128:131]
	v_mfma_f32_16x16x32_bf16 v[124:127], v[140:143], v[214:217], v[124:127]
	v_mfma_f32_16x16x32_bf16 v[116:119], v[132:135], v[222:225], v[116:119]
	v_mfma_f32_16x16x32_bf16 v[108:111], v[140:143], v[222:225], v[108:111]
	v_mfma_f32_16x16x32_bf16 v[100:103], v[132:135], v[230:233], v[100:103]
	v_mfma_f32_16x16x32_bf16 v[92:95], v[140:143], v[230:233], v[92:95]
	v_mfma_f32_16x16x32_bf16 v[84:87], v[132:135], v[238:241], v[84:87]
	v_mfma_f32_16x16x32_bf16 v[76:79], v[140:143], v[238:241], v[76:79]
	v_mfma_f32_16x16x32_bf16 v[128:131], v[136:139], v[218:221], v[128:131]
	v_mfma_f32_16x16x32_bf16 v[124:127], v[144:147], v[218:221], v[124:127]
	v_mfma_f32_16x16x32_bf16 v[116:119], v[136:139], v[226:229], v[116:119]
	v_mfma_f32_16x16x32_bf16 v[108:111], v[144:147], v[226:229], v[108:111]
	v_mfma_f32_16x16x32_bf16 v[100:103], v[136:139], v[234:237], v[100:103]
	v_mfma_f32_16x16x32_bf16 v[92:95], v[144:147], v[234:237], v[92:95]
	v_mfma_f32_16x16x32_bf16 v[84:87], v[136:139], v[242:245], v[84:87]
	v_mfma_f32_16x16x32_bf16 v[76:79], v[144:147], v[242:245], v[76:79]
	v_mfma_f32_16x16x32_bf16 v[120:123], v[158:161], v[214:217], v[120:123]
	v_mfma_f32_16x16x32_bf16 v[112:115], v[206:209], v[214:217], v[112:115]
	v_mfma_f32_16x16x32_bf16 v[104:107], v[158:161], v[222:225], v[104:107]
	v_mfma_f32_16x16x32_bf16 v[96:99], v[206:209], v[222:225], v[96:99]
	v_mfma_f32_16x16x32_bf16 v[88:91], v[158:161], v[230:233], v[88:91]
	v_mfma_f32_16x16x32_bf16 v[80:83], v[206:209], v[230:233], v[80:83]
	v_mfma_f32_16x16x32_bf16 v[72:75], v[158:161], v[238:241], v[72:75]
	v_mfma_f32_16x16x32_bf16 v[68:71], v[206:209], v[238:241], v[68:71]
	v_mfma_f32_16x16x32_bf16 v[120:123], v[174:177], v[218:221], v[120:123]
	v_mfma_f32_16x16x32_bf16 v[112:115], v[210:213], v[218:221], v[112:115]
	v_mfma_f32_16x16x32_bf16 v[104:107], v[174:177], v[226:229], v[104:107]
	v_mfma_f32_16x16x32_bf16 v[96:99], v[210:213], v[226:229], v[96:99]
	v_mfma_f32_16x16x32_bf16 v[88:91], v[174:177], v[234:237], v[88:91]
	v_mfma_f32_16x16x32_bf16 v[80:83], v[210:213], v[234:237], v[80:83]
	v_mfma_f32_16x16x32_bf16 v[72:75], v[174:177], v[242:245], v[72:75]
	v_mfma_f32_16x16x32_bf16 v[68:71], v[210:213], v[242:245], v[68:71]
	s_setprio 3
	s_barrier
; #define PG8_STAGE(bufoff, gbase, voff) do { _Pragma("unroll") for (int _i = 0; _i < 2; ++_i) \
;         __builtin_amdgcn_global_load_lds((const unsigned*)((const char*)(gbase) + (voff)[_i]), (PG8_LAS unsigned*)(lds + (bufoff) + ldsw + _i * 8192), 16, 0, 0); } while (0)
; #define PG8_LDA(dst, b, h) do { _Pragma("unroll") for (int m = 0; m < 4; ++m) _Pragma("unroll") for (int k = 0; k < 2; ++k) dst[m][k] = *(const PG8_LAS bf16x8*)(lds + PG8_SA(b, h) + aoff + m * 2048 + k * 1024); } while (0)
; #define PG8_LDB(dst, b, h) do { _Pragma("unroll") for (int n = 0; n < 2; ++n) _Pragma("unroll") for (int k = 0; k < 2; ++k) dst[n][k] = *(const PG8_LAS bf16x8*)(lds + PG8_SB(b, h) + boff + n * 2048 + k * 1024); } while (0)
; #define PG8_MMA(ai, bj, At, Bt) do { __builtin_amdgcn_s_setprio(1); _Pragma("unroll") for (int m = 0; m < 4; ++m) _Pragma("unroll") for (int n = 0; n < 2; ++n) _Pragma("unroll") for (int k = 0; k < 2; ++k) \
;         acc[ai][bj][m][n] = __builtin_amdgcn_mfma_f32_16x16x32_bf16(Bt[n][k], At[m][k], acc[ai][bj][m][n], 0, 0, 0); __builtin_amdgcn_s_setprio(0); } while (0)
; #define PG8_WAIT_V(n) asm volatile("s_waitcnt vmcnt(" #n ")" ::: "memory")
; #define PG8_WAIT_L(n) asm volatile("s_waitcnt lgkmcnt(" #n ")" ::: "memory")
; #define PG8_BAR __builtin_amdgcn_s_barrier()
; #define PG8_SCHED __builtin_amdgcn_sched_barrier(0)
; template <class Epi, class Sched, bool ALIGN_EPI = false, bool SP2 = false>
; __device__ __forceinline__ void gemm_phase(PG8_LAS unsigned char* lds, const Gemm g, const Sched& S, const Epi& E) {
;     ...
;             PG8_LDA(At, 0, 1); PG8_STAGE(PG8_SB(0, 0), b2, voffB); PG8_STAGE(PG8_SB(0, 1), b2 + hstep, voffB); PG8_STAGE(PG8_SA(0, 0), a2, voffA);
;             PG8_WAIT_V(8); PG8_WAIT_L(0); PG8_BAR; PG8_MMA(1, 0, At, B0); PG8_MMA(1, 1, At, B1); PG8_BAR; PG8_SCHED;
;             PG8_LDB(B0, 1, 0); PG8_LDB(B1, 1, 1); PG8_SCHED; PG8_LDA(At, 1, 0); PG8_STAGE(PG8_SA(0, 1), a2 + hstep, voffA);
	s_add_i32 s64, s64, s46
	s_mov_b32 m0, s64
	ds_read_b128 v[214:217], v204 offset:16384
	ds_read_b128 v[218:221], v204 offset:17408
	ds_read_b128 v[222:225], v204 offset:18432
	ds_read_b128 v[226:229], v204 offset:19456
	ds_read_b128 v[230:233], v204 offset:20480
	ds_read_b128 v[234:237], v204 offset:21504
	ds_read_b128 v[238:241], v204 offset:22528
	ds_read_b128 v[242:245], v204 offset:23552
	global_load_lds_dwordx4 v2, s[42:43]
	s_add_i32 m0, s64, 0x2000
	s_add_u32 s64, s42, 0x80000
	s_addc_u32 s65, s43, 0
	s_add_i32 s66, s66, s46
	global_load_lds_dwordx4 v148, s[42:43]
	s_mov_b32 m0, s66
	s_nop 0
	global_load_lds_dwordx4 v2, s[64:65]
	s_add_i32 m0, s66, 0x2000
	s_nop 0
	global_load_lds_dwordx4 v148, s[64:65]
	s_mov_b32 m0, s39
	s_nop 0
	global_load_lds_dwordx4 v152, s[44:45]
	s_mov_b32 m0, s51
	s_nop 0
	global_load_lds_dwordx4 v150, s[44:45]
	s_nop 0
	s_waitcnt vmcnt(8) lgkmcnt(0)
	s_barrier
	s_setprio 0
	s_waitcnt lgkmcnt(0)
	v_mfma_f32_16x16x32_bf16 v[64:67], v[132:135], v[214:217], v[64:67]
	v_mfma_f32_16x16x32_bf16 v[60:63], v[140:143], v[214:217], v[60:63]
	v_mfma_f32_16x16x32_bf16 v[52:55], v[132:135], v[222:225], v[52:55]
	v_mfma_f32_16x16x32_bf16 v[44:47], v[140:143], v[222:225], v[44:47]
	v_mfma_f32_16x16x32_bf16 v[36:39], v[132:135], v[230:233], v[36:39]
	v_mfma_f32_16x16x32_bf16 v[28:31], v[140:143], v[230:233], v[28:31]
	v_mfma_f32_16x16x32_bf16 v[20:23], v[132:135], v[238:241], v[20:23]
	v_mfma_f32_16x16x32_bf16 v[12:15], v[140:143], v[238:241], v[12:15]
	v_mfma_f32_16x16x32_bf16 v[64:67], v[136:139], v[218:221], v[64:67]
	v_mfma_f32_16x16x32_bf16 v[60:63], v[144:147], v[218:221], v[60:63]
	v_mfma_f32_16x16x32_bf16 v[52:55], v[136:139], v[226:229], v[52:55]
	v_mfma_f32_16x16x32_bf16 v[44:47], v[144:147], v[226:229], v[44:47]
	v_mfma_f32_16x16x32_bf16 v[36:39], v[136:139], v[234:237], v[36:39]
	v_mfma_f32_16x16x32_bf16 v[28:31], v[144:147], v[234:237], v[28:31]
	v_mfma_f32_16x16x32_bf16 v[20:23], v[136:139], v[242:245], v[20:23]
	v_mfma_f32_16x16x32_bf16 v[12:15], v[144:147], v[242:245], v[12:15]
	v_mfma_f32_16x16x32_bf16 v[56:59], v[158:161], v[214:217], v[56:59]
	ds_read_b128 v[132:135], v249 offset:32768
	v_mfma_f32_16x16x32_bf16 v[48:51], v[206:209], v[214:217], v[48:51]
	ds_read_b128 v[136:139], v249 offset:33792
	v_mfma_f32_16x16x32_bf16 v[40:43], v[158:161], v[222:225], v[40:43]
	ds_read_b128 v[140:143], v249 offset:34816
	v_mfma_f32_16x16x32_bf16 v[32:35], v[206:209], v[222:225], v[32:35]
	ds_read_b128 v[144:147], v249 offset:35840
	v_mfma_f32_16x16x32_bf16 v[24:27], v[158:161], v[230:233], v[24:27]
	v_mfma_f32_16x16x32_bf16 v[16:19], v[206:209], v[230:233], v[16:19]
	v_mfma_f32_16x16x32_bf16 v[8:11], v[158:161], v[238:241], v[8:11]
	v_mfma_f32_16x16x32_bf16 v[4:7], v[206:209], v[238:241], v[4:7]
	v_mfma_f32_16x16x32_bf16 v[56:59], v[174:177], v[218:221], v[56:59]
	v_mfma_f32_16x16x32_bf16 v[48:51], v[210:213], v[218:221], v[48:51]
	v_mfma_f32_16x16x32_bf16 v[40:43], v[174:177], v[226:229], v[40:43]
	v_mfma_f32_16x16x32_bf16 v[32:35], v[210:213], v[226:229], v[32:35]
	v_mfma_f32_16x16x32_bf16 v[24:27], v[174:177], v[234:237], v[24:27]
	v_mfma_f32_16x16x32_bf16 v[16:19], v[210:213], v[234:237], v[16:19]
	v_mfma_f32_16x16x32_bf16 v[8:11], v[174:177], v[242:245], v[8:11]
	v_mfma_f32_16x16x32_bf16 v[4:7], v[210:213], v[242:245], v[4:7]
	s_setprio 3
	s_barrier
	s_add_i32 s64, 0, 0x18000
	s_add_i32 s65, 0, 0x1c000
	ds_read_b128 v[158:161], v249 offset:49152
	ds_read_b128 v[174:177], v249 offset:50176
	ds_read_b128 v[206:209], v249 offset:51200
	ds_read_b128 v[210:213], v249 offset:52224
	s_add_u32 s100, s44, 0x80
	s_addc_u32 s101, s45, 0
	s_add_u32 s44, s44, 0x80000
	s_addc_u32 s45, s45, 0
	s_mov_b32 m0, s52
	ds_read_b128 v[214:217], v204 offset:32768
	ds_read_b128 v[218:221], v204 offset:33792
	ds_read_b128 v[222:225], v204 offset:34816
	ds_read_b128 v[226:229], v204 offset:35840
	ds_read_b128 v[230:233], v204 offset:36864
	ds_read_b128 v[234:237], v204 offset:37888
	ds_read_b128 v[238:241], v204 offset:38912
	ds_read_b128 v[242:245], v204 offset:39936
	global_load_lds_dwordx4 v152, s[44:45]
	s_mov_b32 m0, s53
	s_nop 0
	global_load_lds_dwordx4 v150, s[44:45]
	s_nop 0
	s_waitcnt vmcnt(8) lgkmcnt(0)
	s_barrier
; #define PG8_STAGE(bufoff, gbase, voff) do { _Pragma("unroll") for (int _i = 0; _i < 2; ++_i) \
;         __builtin_amdgcn_global_load_lds((const unsigned*)((const char*)(gbase) + (voff)[_i]), (PG8_LAS unsigned*)(lds + (bufoff) + ldsw + _i * 8192), 16, 0, 0); } while (0)
; #define PG8_LDA(dst, b, h) do { _Pragma("unroll") for (int m = 0; m < 4; ++m) _Pragma("unroll") for (int k = 0; k < 2; ++k) dst[m][k] = *(const PG8_LAS bf16x8*)(lds + PG8_SA(b, h) + aoff + m * 2048 + k * 1024); } while (0)
; #define PG8_MMA(ai, bj, At, Bt) do { __builtin_amdgcn_s_setprio(1); _Pragma("unroll") for (int m = 0; m < 4; ++m) _Pragma("unroll") for (int n = 0; n < 2; ++n) _Pragma("unroll") for (int k = 0; k < 2; ++k) \
;         acc[ai][bj][m][n] = __builtin_amdgcn_mfma_f32_16x16x32_bf16(Bt[n][k], At[m][k], acc[ai][bj][m][n], 0, 0, 0); __builtin_amdgcn_s_setprio(0); } while (0)
; #define PG8_WAIT_V(n) asm volatile("s_waitcnt vmcnt(" #n ")" ::: "memory")
; #define PG8_WAIT_L(n) asm volatile("s_waitcnt lgkmcnt(" #n ")" ::: "memory")
; #define PG8_BAR __builtin_amdgcn_s_barrier()
; #define PG8_SCHED __builtin_amdgcn_sched_barrier(0)
; template <class Epi, class Sched, bool ALIGN_EPI = false, bool SP2 = false>
; __device__ __forceinline__ void gemm_phase(PG8_LAS unsigned char* lds, const Gemm g, const Sched& S, const Epi& E) {
;     ...
;         for (int t = 0; t < nt; t += 2) {
;             const bool last = (t == nt - 2);
;             const char* a1 = cA + (size_t)(t + 1) * kstep;
;             const char* a2 = last ? nA : cA + (size_t)(t + 2) * kstep; const char* b2 = last ? nB : cB + (size_t)(t + 2) * kstep;
;             const char* a3 = a2 + kstep; const char* b3 = b2 + kstep;
;     ...
;             PG8_WAIT_V(8); PG8_WAIT_L(0); PG8_BAR; PG8_MMA(0, 0, At, B0); PG8_MMA(0, 1, At, B1); PG8_BAR; PG8_SCHED;
;             PG8_LDA(At, 1, 1); PG8_STAGE(PG8_SB(1, 0), b3, voffB); PG8_STAGE(PG8_SB(1, 1), b3 + hstep, voffB); PG8_STAGE(PG8_SA(1, 0), a3, voffA);
;             PG8_WAIT_V(8); PG8_WAIT_L(0); PG8_BAR; PG8_MMA(1, 0, At, B0); PG8_MMA(1, 1, At, B1); PG8_BAR; PG8_SCHED;
	s_setprio 0
	s_waitcnt lgkmcnt(0)
	v_mfma_f32_16x16x32_bf16 v[128:131], v[132:135], v[214:217], v[128:131]
	v_mfma_f32_16x16x32_bf16 v[124:127], v[140:143], v[214:217], v[124:127]
	v_mfma_f32_16x16x32_bf16 v[116:119], v[132:135], v[222:225], v[116:119]
	v_mfma_f32_16x16x32_bf16 v[108:111], v[140:143], v[222:225], v[108:111]
	v_mfma_f32_16x16x32_bf16 v[100:103], v[132:135], v[230:233], v[100:103]
	v_mfma_f32_16x16x32_bf16 v[92:95], v[140:143], v[230:233], v[92:95]
	v_mfma_f32_16x16x32_bf16 v[84:87], v[132:135], v[238:241], v[84:87]
	v_mfma_f32_16x16x32_bf16 v[76:79], v[140:143], v[238:241], v[76:79]
	v_mfma_f32_16x16x32_bf16 v[128:131], v[136:139], v[218:221], v[128:131]
	v_mfma_f32_16x16x32_bf16 v[124:127], v[144:147], v[218:221], v[124:127]
	v_mfma_f32_16x16x32_bf16 v[116:119], v[136:139], v[226:229], v[116:119]
	v_mfma_f32_16x16x32_bf16 v[108:111], v[144:147], v[226:229], v[108:111]
	v_mfma_f32_16x16x32_bf16 v[100:103], v[136:139], v[234:237], v[100:103]
	v_mfma_f32_16x16x32_bf16 v[92:95], v[144:147], v[234:237], v[92:95]
	v_mfma_f32_16x16x32_bf16 v[84:87], v[136:139], v[242:245], v[84:87]
	v_mfma_f32_16x16x32_bf16 v[76:79], v[144:147], v[242:245], v[76:79]
	v_mfma_f32_16x16x32_bf16 v[120:123], v[158:161], v[214:217], v[120:123]
	v_mfma_f32_16x16x32_bf16 v[112:115], v[206:209], v[214:217], v[112:115]
	v_mfma_f32_16x16x32_bf16 v[104:107], v[158:161], v[222:225], v[104:107]
	v_mfma_f32_16x16x32_bf16 v[96:99], v[206:209], v[222:225], v[96:99]
	v_mfma_f32_16x16x32_bf16 v[88:91], v[158:161], v[230:233], v[88:91]
	v_mfma_f32_16x16x32_bf16 v[80:83], v[206:209], v[230:233], v[80:83]
	v_mfma_f32_16x16x32_bf16 v[72:75], v[158:161], v[238:241], v[72:75]
	v_mfma_f32_16x16x32_bf16 v[68:71], v[206:209], v[238:241], v[68:71]
	v_mfma_f32_16x16x32_bf16 v[120:123], v[174:177], v[218:221], v[120:123]
	v_mfma_f32_16x16x32_bf16 v[112:115], v[210:213], v[218:221], v[112:115]
	v_mfma_f32_16x16x32_bf16 v[104:107], v[174:177], v[226:229], v[104:107]
	v_mfma_f32_16x16x32_bf16 v[96:99], v[210:213], v[226:229], v[96:99]
	v_mfma_f32_16x16x32_bf16 v[88:91], v[174:177], v[234:237], v[88:91]
	v_mfma_f32_16x16x32_bf16 v[80:83], v[210:213], v[234:237], v[80:83]
	v_mfma_f32_16x16x32_bf16 v[72:75], v[174:177], v[242:245], v[72:75]
	v_mfma_f32_16x16x32_bf16 v[68:71], v[210:213], v[242:245], v[68:71]
	s_setprio 3
	s_barrier
	s_add_i32 s44, s64, s46
	s_add_i32 m0, s44, 0xffffff80
	ds_read_b128 v[214:217], v204 offset:49152
	ds_read_b128 v[218:221], v204 offset:50176
	ds_read_b128 v[222:225], v204 offset:51200
	ds_read_b128 v[226:229], v204 offset:52224
	ds_read_b128 v[230:233], v204 offset:53248
	ds_read_b128 v[234:237], v204 offset:54272
	ds_read_b128 v[238:241], v204 offset:55296
	ds_read_b128 v[242:245], v204 offset:56320
	global_load_lds_dwordx4 v2, s[42:43] offset:128
	s_add_i32 m0, s44, 0x1f80
	s_add_i32 s44, s65, s46
	global_load_lds_dwordx4 v148, s[42:43] offset:128
	s_add_u32 s42, s42, 0x80080
	s_addc_u32 s43, s43, 0
	s_mov_b32 m0, s44
	s_nop 0
	global_load_lds_dwordx4 v2, s[42:43]
	s_add_i32 m0, s44, 0x2000
	s_nop 0
	global_load_lds_dwordx4 v148, s[42:43]
	s_mov_b32 m0, s54
	s_nop 0
	global_load_lds_dwordx4 v152, s[100:101]
	s_mov_b32 m0, s55
	s_nop 0
	global_load_lds_dwordx4 v150, s[100:101]
	s_nop 0
	s_nop 0
	s_nop 0
	s_nop 0
	s_nop 0
	s_waitcnt vmcnt(8) lgkmcnt(0)
	s_barrier
	s_setprio 0
	s_waitcnt lgkmcnt(0)
	v_mfma_f32_16x16x32_bf16 v[64:67], v[132:135], v[214:217], v[64:67]
	v_mfma_f32_16x16x32_bf16 v[60:63], v[140:143], v[214:217], v[60:63]
	v_mfma_f32_16x16x32_bf16 v[52:55], v[132:135], v[222:225], v[52:55]
	v_mfma_f32_16x16x32_bf16 v[44:47], v[140:143], v[222:225], v[44:47]
	v_mfma_f32_16x16x32_bf16 v[36:39], v[132:135], v[230:233], v[36:39]
	v_mfma_f32_16x16x32_bf16 v[28:31], v[140:143], v[230:233], v[28:31]
	v_mfma_f32_16x16x32_bf16 v[20:23], v[132:135], v[238:241], v[20:23]
	v_mfma_f32_16x16x32_bf16 v[12:15], v[140:143], v[238:241], v[12:15]
	v_mfma_f32_16x16x32_bf16 v[64:67], v[136:139], v[218:221], v[64:67]
	v_mfma_f32_16x16x32_bf16 v[60:63], v[144:147], v[218:221], v[60:63]
	v_mfma_f32_16x16x32_bf16 v[52:55], v[136:139], v[226:229], v[52:55]
	v_mfma_f32_16x16x32_bf16 v[44:47], v[144:147], v[226:229], v[44:47]
	v_mfma_f32_16x16x32_bf16 v[36:39], v[136:139], v[234:237], v[36:39]
	v_mfma_f32_16x16x32_bf16 v[28:31], v[144:147], v[234:237], v[28:31]
	v_mfma_f32_16x16x32_bf16 v[20:23], v[136:139], v[242:245], v[20:23]
	v_mfma_f32_16x16x32_bf16 v[12:15], v[144:147], v[242:245], v[12:15]
	v_mfma_f32_16x16x32_bf16 v[56:59], v[158:161], v[214:217], v[56:59]
	ds_read_b128 v[132:135], v249
	v_mfma_f32_16x16x32_bf16 v[48:51], v[206:209], v[214:217], v[48:51]
	ds_read_b128 v[136:139], v249 offset:1024
	v_mfma_f32_16x16x32_bf16 v[40:43], v[158:161], v[222:225], v[40:43]
	ds_read_b128 v[140:143], v249 offset:2048
	v_mfma_f32_16x16x32_bf16 v[32:35], v[206:209], v[222:225], v[32:35]
	s_add_i32 s63, s63, 2
	s_add_u32 s40, s40, 0x100
	s_addc_u32 s41, s41, 0
	s_add_u32 s35, s35, 0x100
	s_addc_u32 s62, s62, 0
	s_add_u32 s42, s40, 0xfff80080
	s_addc_u32 s43, s41, -1
	s_add_i32 s64, 0, 0x10000
	s_cmp_eq_u32 s63, 28
	s_cselect_b32 s45, s5, s43
	s_cselect_b32 s44, s4, s42
	s_cselect_b32 s43, s37, s62
	s_cselect_b32 s42, s36, s35
	s_add_i32 s66, 0, 0x14000
	ds_read_b128 v[144:147], v249 offset:3072
	v_mfma_f32_16x16x32_bf16 v[24:27], v[158:161], v[230:233], v[24:27]
	v_mfma_f32_16x16x32_bf16 v[16:19], v[206:209], v[230:233], v[16:19]
	v_mfma_f32_16x16x32_bf16 v[8:11], v[158:161], v[238:241], v[8:11]
	v_mfma_f32_16x16x32_bf16 v[4:7], v[206:209], v[238:241], v[4:7]
	v_mfma_f32_16x16x32_bf16 v[56:59], v[174:177], v[218:221], v[56:59]
	v_mfma_f32_16x16x32_bf16 v[48:51], v[210:213], v[218:221], v[48:51]
	v_mfma_f32_16x16x32_bf16 v[40:43], v[174:177], v[226:229], v[40:43]
	v_mfma_f32_16x16x32_bf16 v[32:35], v[210:213], v[226:229], v[32:35]
	v_mfma_f32_16x16x32_bf16 v[24:27], v[174:177], v[234:237], v[24:27]
	v_mfma_f32_16x16x32_bf16 v[16:19], v[210:213], v[234:237], v[16:19]
	v_mfma_f32_16x16x32_bf16 v[8:11], v[174:177], v[242:245], v[8:11]
	v_mfma_f32_16x16x32_bf16 v[4:7], v[210:213], v[242:245], v[4:7]
	s_setprio 3
	s_barrier
	s_cmp_gt_u32 s63, 29
	s_cbranch_scc0 .LBB0_674
	s_and_b64 vcc, exec, s[30:31]
	s_cbranch_vccz .LBB0_677
	s_barrier

;     __device__ __forceinline__ bool next(int i, Unit& u) const { if (!StaticOrder::next(i / 3, u)) return false; u.aux = i % 3; return true; }
; #define PG8_STAGE(bufoff, gbase, voff) do { _Pragma("unroll") for (int _i = 0; _i < 2; ++_i) \
;         __builtin_amdgcn_global_load_lds((const unsigned*)((const char*)(gbase) + (voff)[_i]), (PG8_LAS unsigned*)(lds + (bufoff) + ldsw + _i * 8192), 16, 0, 0); } while (0)
; #define PG8_LDA(dst, b, h) do { _Pragma("unroll") for (int m = 0; m < 4; ++m) _Pragma("unroll") for (int k = 0; k < 2; ++k) dst[m][k] = *(const PG8_LAS bf16x8*)(lds + PG8_SA(b, h) + aoff + m * 2048 + k * 1024); } while (0)
; #define PG8_LDB(dst, b, h) do { _Pragma("unroll") for (int n = 0; n < 2; ++n) _Pragma("unroll") for (int k = 0; k < 2; ++k) dst[n][k] = *(const PG8_LAS bf16x8*)(lds + PG8_SB(b, h) + boff + n * 2048 + k * 1024); } while (0)
; #define PG8_MMA(ai, bj, At, Bt) do { __builtin_amdgcn_s_setprio(1); _Pragma("unroll") for (int m = 0; m < 4; ++m) _Pragma("unroll") for (int n = 0; n < 2; ++n) _Pragma("unroll") for (int k = 0; k < 2; ++k) \
;         acc[ai][bj][m][n] = __builtin_amdgcn_mfma_f32_16x16x32_bf16(Bt[n][k], At[m][k], acc[ai][bj][m][n], 0, 0, 0); __builtin_amdgcn_s_setprio(0); } while (0)
; #define PG8_WAIT_V(n) asm volatile("s_waitcnt vmcnt(" #n ")" ::: "memory")
; #define PG8_BAR __builtin_amdgcn_s_barrier()
; template <class Epi, class Sched, bool ALIGN_EPI = false, bool SP2 = false>
; __device__ __forceinline__ void gemm_phase(PG8_LAS unsigned char* lds, const Gemm g, const Sched& S, const Epi& E) {
;     ...
;         const bool has_next = S.next(ui + 1, nxt);
;         const char* nA = cA; const char* nB = cB; if (has_next) S.bases(g, nxt, tstep, nA, nB);
;         for (int t = 0; t < nt; t += 2) {
;             const bool last = (t == nt - 2);
;             const char* a1 = cA + (size_t)(t + 1) * kstep;
;             const char* a2 = last ? nA : cA + (size_t)(t + 2) * kstep; const char* b2 = last ? nB : cB + (size_t)(t + 2) * kstep;
;             const char* a3 = a2 + kstep; const char* b3 = b2 + kstep;
;             if (last && has_next) S.a_ready(nxt);
;             if constexpr (SP2) {
;             PG8_LDB(B0, 0, 0); PG8_LDB(B1, 0, 1); PG8_SCHED; PG8_LDA(At, 0, 0); PG8_STAGE(PG8_SA(1, 1), a1 + hstep, voffA);
;             PG8_WAIT_V(8); PG8_WAIT_L(0); PG8_BAR; PG8_MMA(0, 0, At, B0); PG8_MMA(0, 1, At, B1); PG8_BAR; PG8_SCHED;
.LBB0_2095:
	s_add_u32 s40, s40, 0x40080
	s_addc_u32 s41, s41, 0
	s_add_u32 s11, s42, 0x100
	s_addc_u32 s13, s43, 0
	s_mov_b32 s26, -2
	v_add_u32_e32 v175, 0x10000, v173
	ds_read_b128 v[134:137], v175
	ds_read_b128 v[138:141], v175 offset:1024
	ds_read_b128 v[154:157], v175 offset:2048
	ds_read_b128 v[158:161], v175 offset:3072
	s_add_u32 s27, s40, 0xfffc0080
	s_addc_u32 s29, s41, -1
	s_add_i32 s31, 0, 0x10000
	s_cmp_eq_u32 s26, 12
	s_cselect_b32 s45, s1, s29
	s_cselect_b32 s44, s0, s27
	s_cselect_b32 s43, s35, s13
	s_cselect_b32 s42, s34, s11
	s_add_i32 s27, 0, 0x14000
	.p2align 6
	s_nop 0
.LBB0_2096:
	ds_read_b128 v[178:181], v175 offset:16384
	ds_read_b128 v[204:207], v175 offset:17408
	ds_read_b128 v[208:211], v175 offset:18432
	ds_read_b128 v[212:215], v175 offset:19456
	s_add_i32 m0, s55, 0xc000
	ds_read_b128 v[216:219], v177
	ds_read_b128 v[220:223], v177 offset:1024
	ds_read_b128 v[224:227], v177 offset:2048
	ds_read_b128 v[228:231], v177 offset:3072
	ds_read_b128 v[232:235], v177 offset:4096
	ds_read_b128 v[236:239], v177 offset:5120
	ds_read_b128 v[240:243], v177 offset:6144
	ds_read_b128 v[244:247], v177 offset:7168
	global_load_lds_dwordx4 v150, s[40:41]
	s_add_i32 m0, s55, 0xe000
	s_nop 0
	global_load_lds_dwordx4 v152, s[40:41]
	s_nop 0
	s_waitcnt vmcnt(8) lgkmcnt(0)
	s_barrier
	s_setprio 0
	s_waitcnt lgkmcnt(0)
	v_mfma_f32_16x16x32_bf16 v[130:133], v[134:137], v[216:219], v[130:133]
	v_mfma_f32_16x16x32_bf16 v[126:129], v[154:157], v[216:219], v[126:129]
	v_mfma_f32_16x16x32_bf16 v[122:125], v[134:137], v[224:227], v[122:125]
	v_mfma_f32_16x16x32_bf16 v[118:121], v[154:157], v[224:227], v[118:121]
	v_mfma_f32_16x16x32_bf16 v[114:117], v[134:137], v[232:235], v[114:117]
	v_mfma_f32_16x16x32_bf16 v[110:113], v[154:157], v[232:235], v[110:113]
	v_mfma_f32_16x16x32_bf16 v[106:109], v[134:137], v[240:243], v[106:109]
	v_mfma_f32_16x16x32_bf16 v[102:105], v[154:157], v[240:243], v[102:105]
	v_mfma_f32_16x16x32_bf16 v[130:133], v[138:141], v[220:223], v[130:133]
	v_mfma_f32_16x16x32_bf16 v[126:129], v[158:161], v[220:223], v[126:129]
	v_mfma_f32_16x16x32_bf16 v[122:125], v[138:141], v[228:231], v[122:125]
	v_mfma_f32_16x16x32_bf16 v[118:121], v[158:161], v[228:231], v[118:121]
	v_mfma_f32_16x16x32_bf16 v[114:117], v[138:141], v[236:239], v[114:117]
	v_mfma_f32_16x16x32_bf16 v[110:113], v[158:161], v[236:239], v[110:113]
	v_mfma_f32_16x16x32_bf16 v[106:109], v[138:141], v[244:247], v[106:109]
	v_mfma_f32_16x16x32_bf16 v[102:105], v[158:161], v[244:247], v[102:105]
	v_mfma_f32_16x16x32_bf16 v[98:101], v[178:181], v[216:219], v[98:101]
	v_mfma_f32_16x16x32_bf16 v[94:97], v[208:211], v[216:219], v[94:97]
	v_mfma_f32_16x16x32_bf16 v[90:93], v[178:181], v[224:227], v[90:93]
	v_mfma_f32_16x16x32_bf16 v[86:89], v[208:211], v[224:227], v[86:89]
	v_mfma_f32_16x16x32_bf16 v[82:85], v[178:181], v[232:235], v[82:85]
	v_mfma_f32_16x16x32_bf16 v[78:81], v[208:211], v[232:235], v[78:81]
	v_mfma_f32_16x16x32_bf16 v[74:77], v[178:181], v[240:243], v[74:77]
	v_mfma_f32_16x16x32_bf16 v[70:73], v[208:211], v[240:243], v[70:73]
	v_mfma_f32_16x16x32_bf16 v[98:101], v[204:207], v[220:223], v[98:101]
	v_mfma_f32_16x16x32_bf16 v[94:97], v[212:215], v[220:223], v[94:97]
	v_mfma_f32_16x16x32_bf16 v[90:93], v[204:207], v[228:231], v[90:93]
	v_mfma_f32_16x16x32_bf16 v[86:89], v[212:215], v[228:231], v[86:89]
	v_mfma_f32_16x16x32_bf16 v[82:85], v[204:207], v[236:239], v[82:85]
	v_mfma_f32_16x16x32_bf16 v[78:81], v[212:215], v[236:239], v[78:81]
	v_mfma_f32_16x16x32_bf16 v[74:77], v[204:207], v[244:247], v[74:77]
	v_mfma_f32_16x16x32_bf16 v[70:73], v[212:215], v[244:247], v[70:73]
	s_setprio 3
	s_barrier
	s_add_i32 s29, s31, s54
	s_mov_b32 m0, s29
	ds_read_b128 v[216:219], v177 offset:16384
	ds_read_b128 v[220:223], v177 offset:17408
	ds_read_b128 v[224:227], v177 offset:18432
	ds_read_b128 v[228:231], v177 offset:19456
	ds_read_b128 v[232:235], v177 offset:20480
	ds_read_b128 v[236:239], v177 offset:21504
	ds_read_b128 v[240:243], v177 offset:22528
	ds_read_b128 v[244:247], v177 offset:23552
	global_load_lds_dwordx4 v144, s[42:43]
	s_add_i32 m0, s29, 0x2000
	s_add_u32 s64, s42, 0x40000
	s_addc_u32 s65, s43, 0
	s_add_i32 s27, s27, s54
	global_load_lds_dwordx4 v148, s[42:43]
	s_mov_b32 m0, s27
	s_nop 0
	global_load_lds_dwordx4 v144, s[64:65]
	s_add_i32 m0, s27, 0x2000
	s_nop 0
	global_load_lds_dwordx4 v148, s[64:65]
	s_mov_b32 m0, s55
	s_nop 0
	global_load_lds_dwordx4 v142, s[44:45]
	s_mov_b32 m0, s56
	s_nop 0
	global_load_lds_dwordx4 v146, s[44:45]
	s_nop 0
	s_waitcnt vmcnt(8) lgkmcnt(0)
	s_barrier
; #define PG8_STAGE(bufoff, gbase, voff) do { _Pragma("unroll") for (int _i = 0; _i < 2; ++_i) \
;         __builtin_amdgcn_global_load_lds((const unsigned*)((const char*)(gbase) + (voff)[_i]), (PG8_LAS unsigned*)(lds + (bufoff) + ldsw + _i * 8192), 16, 0, 0); } while (0)
; #define PG8_LDA(dst, b, h) do { _Pragma("unroll") for (int m = 0; m < 4; ++m) _Pragma("unroll") for (int k = 0; k < 2; ++k) dst[m][k] = *(const PG8_LAS bf16x8*)(lds + PG8_SA(b, h) + aoff + m * 2048 + k * 1024); } while (0)
; #define PG8_LDB(dst, b, h) do { _Pragma("unroll") for (int n = 0; n < 2; ++n) _Pragma("unroll") for (int k = 0; k < 2; ++k) dst[n][k] = *(const PG8_LAS bf16x8*)(lds + PG8_SB(b, h) + boff + n * 2048 + k * 1024); } while (0)
; #define PG8_MMA(ai, bj, At, Bt) do { __builtin_amdgcn_s_setprio(1); _Pragma("unroll") for (int m = 0; m < 4; ++m) _Pragma("unroll") for (int n = 0; n < 2; ++n) _Pragma("unroll") for (int k = 0; k < 2; ++k) \
;         acc[ai][bj][m][n] = __builtin_amdgcn_mfma_f32_16x16x32_bf16(Bt[n][k], At[m][k], acc[ai][bj][m][n], 0, 0, 0); __builtin_amdgcn_s_setprio(0); } while (0)
; #define PG8_WAIT_V(n) asm volatile("s_waitcnt vmcnt(" #n ")" ::: "memory")
; #define PG8_WAIT_L(n) asm volatile("s_waitcnt lgkmcnt(" #n ")" ::: "memory")
; #define PG8_BAR __builtin_amdgcn_s_barrier()
; #define PG8_SCHED __builtin_amdgcn_sched_barrier(0)
; template <class Epi, class Sched, bool ALIGN_EPI = false, bool SP2 = false>
; __device__ __forceinline__ void gemm_phase(PG8_LAS unsigned char* lds, const Gemm g, const Sched& S, const Epi& E) {
;     ...
;             PG8_WAIT_V(8); PG8_WAIT_L(0); PG8_BAR; PG8_MMA(1, 0, At, B0); PG8_MMA(1, 1, At, B1); PG8_BAR; PG8_SCHED;
;             PG8_LDB(B0, 1, 0); PG8_LDB(B1, 1, 1); PG8_SCHED; PG8_LDA(At, 1, 0); PG8_STAGE(PG8_SA(0, 1), a2 + hstep, voffA);
;             PG8_WAIT_V(8); PG8_WAIT_L(0); PG8_BAR; PG8_MMA(0, 0, At, B0); PG8_MMA(0, 1, At, B1); PG8_BAR; PG8_SCHED;
	s_setprio 0
	s_waitcnt lgkmcnt(0)
	v_mfma_f32_16x16x32_bf16 v[66:69], v[134:137], v[216:219], v[66:69]
	v_mfma_f32_16x16x32_bf16 v[62:65], v[154:157], v[216:219], v[62:65]
	v_mfma_f32_16x16x32_bf16 v[58:61], v[134:137], v[224:227], v[58:61]
	v_mfma_f32_16x16x32_bf16 v[54:57], v[154:157], v[224:227], v[54:57]
	v_mfma_f32_16x16x32_bf16 v[50:53], v[134:137], v[232:235], v[50:53]
	v_mfma_f32_16x16x32_bf16 v[46:49], v[154:157], v[232:235], v[46:49]
	v_mfma_f32_16x16x32_bf16 v[42:45], v[134:137], v[240:243], v[42:45]
	v_mfma_f32_16x16x32_bf16 v[38:41], v[154:157], v[240:243], v[38:41]
	v_mfma_f32_16x16x32_bf16 v[66:69], v[138:141], v[220:223], v[66:69]
	v_mfma_f32_16x16x32_bf16 v[62:65], v[158:161], v[220:223], v[62:65]
	v_mfma_f32_16x16x32_bf16 v[58:61], v[138:141], v[228:231], v[58:61]
	v_mfma_f32_16x16x32_bf16 v[54:57], v[158:161], v[228:231], v[54:57]
	v_mfma_f32_16x16x32_bf16 v[50:53], v[138:141], v[236:239], v[50:53]
	v_mfma_f32_16x16x32_bf16 v[46:49], v[158:161], v[236:239], v[46:49]
	v_mfma_f32_16x16x32_bf16 v[42:45], v[138:141], v[244:247], v[42:45]
	v_mfma_f32_16x16x32_bf16 v[38:41], v[158:161], v[244:247], v[38:41]
	v_mfma_f32_16x16x32_bf16 v[34:37], v[178:181], v[216:219], v[34:37]
	ds_read_b128 v[134:137], v175 offset:32768
	v_mfma_f32_16x16x32_bf16 v[30:33], v[208:211], v[216:219], v[30:33]
	ds_read_b128 v[138:141], v175 offset:33792
	v_mfma_f32_16x16x32_bf16 v[26:29], v[178:181], v[224:227], v[26:29]
	ds_read_b128 v[154:157], v175 offset:34816
	v_mfma_f32_16x16x32_bf16 v[22:25], v[208:211], v[224:227], v[22:25]
	ds_read_b128 v[158:161], v175 offset:35840
	v_mfma_f32_16x16x32_bf16 v[18:21], v[178:181], v[232:235], v[18:21]
	v_mfma_f32_16x16x32_bf16 v[14:17], v[208:211], v[232:235], v[14:17]
	v_mfma_f32_16x16x32_bf16 v[10:13], v[178:181], v[240:243], v[10:13]
	v_mfma_f32_16x16x32_bf16 v[4:7], v[208:211], v[240:243], v[6:9]
	v_mfma_f32_16x16x32_bf16 v[34:37], v[204:207], v[220:223], v[34:37]
	v_mfma_f32_16x16x32_bf16 v[30:33], v[212:215], v[220:223], v[30:33]
	v_mfma_f32_16x16x32_bf16 v[26:29], v[204:207], v[228:231], v[26:29]
	v_mfma_f32_16x16x32_bf16 v[22:25], v[212:215], v[228:231], v[22:25]
	v_mfma_f32_16x16x32_bf16 v[18:21], v[204:207], v[236:239], v[18:21]
	v_mfma_f32_16x16x32_bf16 v[14:17], v[212:215], v[236:239], v[14:17]
	v_mfma_f32_16x16x32_bf16 v[10:13], v[204:207], v[244:247], v[10:13]
	v_mfma_f32_16x16x32_bf16 v[4:7], v[212:215], v[244:247], v[4:7]
	s_setprio 3
	s_barrier
	s_add_i32 s27, 0, 0x18000
	s_add_i32 s29, 0, 0x1c000
	ds_read_b128 v[178:181], v175 offset:49152
	ds_read_b128 v[204:207], v175 offset:50176
	ds_read_b128 v[208:211], v175 offset:51200
	ds_read_b128 v[212:215], v175 offset:52224
	s_add_u32 s100, s44, 0x80
	s_addc_u32 s101, s45, 0
	s_add_u32 s44, s44, 0x40000
	s_addc_u32 s45, s45, 0
	s_mov_b32 m0, s57
	ds_read_b128 v[216:219], v177 offset:32768
	ds_read_b128 v[220:223], v177 offset:33792
	ds_read_b128 v[224:227], v177 offset:34816
	ds_read_b128 v[228:231], v177 offset:35840
	ds_read_b128 v[232:235], v177 offset:36864
	ds_read_b128 v[236:239], v177 offset:37888
	ds_read_b128 v[240:243], v177 offset:38912
	ds_read_b128 v[244:247], v177 offset:39936
	global_load_lds_dwordx4 v142, s[44:45]
	s_mov_b32 m0, s58
	s_nop 0
	global_load_lds_dwordx4 v146, s[44:45]
	s_nop 0
	s_waitcnt vmcnt(8) lgkmcnt(0)
	s_barrier
	s_setprio 0
	s_waitcnt lgkmcnt(0)
	v_mfma_f32_16x16x32_bf16 v[130:133], v[134:137], v[216:219], v[130:133]
	v_mfma_f32_16x16x32_bf16 v[126:129], v[154:157], v[216:219], v[126:129]
	v_mfma_f32_16x16x32_bf16 v[122:125], v[134:137], v[224:227], v[122:125]
	v_mfma_f32_16x16x32_bf16 v[118:121], v[154:157], v[224:227], v[118:121]
	v_mfma_f32_16x16x32_bf16 v[114:117], v[134:137], v[232:235], v[114:117]
	v_mfma_f32_16x16x32_bf16 v[110:113], v[154:157], v[232:235], v[110:113]
	v_mfma_f32_16x16x32_bf16 v[106:109], v[134:137], v[240:243], v[106:109]
	v_mfma_f32_16x16x32_bf16 v[102:105], v[154:157], v[240:243], v[102:105]
	v_mfma_f32_16x16x32_bf16 v[130:133], v[138:141], v[220:223], v[130:133]
	v_mfma_f32_16x16x32_bf16 v[126:129], v[158:161], v[220:223], v[126:129]
	v_mfma_f32_16x16x32_bf16 v[122:125], v[138:141], v[228:231], v[122:125]
	v_mfma_f32_16x16x32_bf16 v[118:121], v[158:161], v[228:231], v[118:121]
	v_mfma_f32_16x16x32_bf16 v[114:117], v[138:141], v[236:239], v[114:117]
	v_mfma_f32_16x16x32_bf16 v[110:113], v[158:161], v[236:239], v[110:113]
	v_mfma_f32_16x16x32_bf16 v[106:109], v[138:141], v[244:247], v[106:109]
	v_mfma_f32_16x16x32_bf16 v[102:105], v[158:161], v[244:247], v[102:105]
	v_mfma_f32_16x16x32_bf16 v[98:101], v[178:181], v[216:219], v[98:101]
	v_mfma_f32_16x16x32_bf16 v[94:97], v[208:211], v[216:219], v[94:97]
	v_mfma_f32_16x16x32_bf16 v[90:93], v[178:181], v[224:227], v[90:93]
	v_mfma_f32_16x16x32_bf16 v[86:89], v[208:211], v[224:227], v[86:89]
	v_mfma_f32_16x16x32_bf16 v[82:85], v[178:181], v[232:235], v[82:85]
	v_mfma_f32_16x16x32_bf16 v[78:81], v[208:211], v[232:235], v[78:81]
	v_mfma_f32_16x16x32_bf16 v[74:77], v[178:181], v[240:243], v[74:77]
	v_mfma_f32_16x16x32_bf16 v[70:73], v[208:211], v[240:243], v[70:73]
	v_mfma_f32_16x16x32_bf16 v[98:101], v[204:207], v[220:223], v[98:101]
	v_mfma_f32_16x16x32_bf16 v[94:97], v[212:215], v[220:223], v[94:97]
	v_mfma_f32_16x16x32_bf16 v[90:93], v[204:207], v[228:231], v[90:93]
	v_mfma_f32_16x16x32_bf16 v[86:89], v[212:215], v[228:231], v[86:89]
	v_mfma_f32_16x16x32_bf16 v[82:85], v[204:207], v[236:239], v[82:85]
	v_mfma_f32_16x16x32_bf16 v[78:81], v[212:215], v[236:239], v[78:81]
	v_mfma_f32_16x16x32_bf16 v[74:77], v[204:207], v[244:247], v[74:77]
	v_mfma_f32_16x16x32_bf16 v[70:73], v[212:215], v[244:247], v[70:73]
	s_setprio 3
	s_barrier
; #define PG8_STAGE(bufoff, gbase, voff) do { _Pragma("unroll") for (int _i = 0; _i < 2; ++_i) \
;         __builtin_amdgcn_global_load_lds((const unsigned*)((const char*)(gbase) + (voff)[_i]), (PG8_LAS unsigned*)(lds + (bufoff) + ldsw + _i * 8192), 16, 0, 0); } while (0)
; #define PG8_LDA(dst, b, h) do { _Pragma("unroll") for (int m = 0; m < 4; ++m) _Pragma("unroll") for (int k = 0; k < 2; ++k) dst[m][k] = *(const PG8_LAS bf16x8*)(lds + PG8_SA(b, h) + aoff + m * 2048 + k * 1024); } while (0)
; #define PG8_MMA(ai, bj, At, Bt) do { __builtin_amdgcn_s_setprio(1); _Pragma("unroll") for (int m = 0; m < 4; ++m) _Pragma("unroll") for (int n = 0; n < 2; ++n) _Pragma("unroll") for (int k = 0; k < 2; ++k) \
;         acc[ai][bj][m][n] = __builtin_amdgcn_mfma_f32_16x16x32_bf16(Bt[n][k], At[m][k], acc[ai][bj][m][n], 0, 0, 0); __builtin_amdgcn_s_setprio(0); } while (0)
; #define PG8_WAIT_V(n) asm volatile("s_waitcnt vmcnt(" #n ")" ::: "memory")
; #define PG8_WAIT_L(n) asm volatile("s_waitcnt lgkmcnt(" #n ")" ::: "memory")
; #define PG8_BAR __builtin_amdgcn_s_barrier()
; #define PG8_SCHED __builtin_amdgcn_sched_barrier(0)
; template <class Epi, class Sched, bool ALIGN_EPI = false, bool SP2 = false>
; __device__ __forceinline__ void gemm_phase(PG8_LAS unsigned char* lds, const Gemm g, const Sched& S, const Epi& E) {
;     ...
;         for (int t = 0; t < nt; t += 2) {
;             const bool last = (t == nt - 2);
;             const char* a1 = cA + (size_t)(t + 1) * kstep;
;             const char* a2 = last ? nA : cA + (size_t)(t + 2) * kstep; const char* b2 = last ? nB : cB + (size_t)(t + 2) * kstep;
;             const char* a3 = a2 + kstep; const char* b3 = b2 + kstep;
;     ...
;             PG8_LDA(At, 1, 1); PG8_STAGE(PG8_SB(1, 0), b3, voffB); PG8_STAGE(PG8_SB(1, 1), b3 + hstep, voffB); PG8_STAGE(PG8_SA(1, 0), a3, voffA);
;             PG8_WAIT_V(8); PG8_WAIT_L(0); PG8_BAR; PG8_MMA(1, 0, At, B0); PG8_MMA(1, 1, At, B1); PG8_BAR; PG8_SCHED;
	s_add_i32 s27, s27, s54
	s_add_i32 m0, s27, 0xffffff80
	ds_read_b128 v[216:219], v177 offset:49152
	ds_read_b128 v[220:223], v177 offset:50176
	ds_read_b128 v[224:227], v177 offset:51200
	ds_read_b128 v[228:231], v177 offset:52224
	ds_read_b128 v[232:235], v177 offset:53248
	ds_read_b128 v[236:239], v177 offset:54272
	ds_read_b128 v[240:243], v177 offset:55296
	ds_read_b128 v[244:247], v177 offset:56320
	global_load_lds_dwordx4 v144, s[42:43] offset:128
	s_add_i32 m0, s27, 0x1f80
	s_add_i32 s27, s29, s54
	global_load_lds_dwordx4 v148, s[42:43] offset:128
	s_add_u32 s42, s42, 0x40080
	s_addc_u32 s43, s43, 0
	s_mov_b32 m0, s27
	s_nop 0
	global_load_lds_dwordx4 v144, s[42:43]
	s_add_i32 m0, s27, 0x2000
	s_nop 0
	global_load_lds_dwordx4 v148, s[42:43]
	s_mov_b32 m0, s61
	s_nop 0
	global_load_lds_dwordx4 v142, s[100:101]
	s_mov_b32 m0, s62
	s_nop 0
	global_load_lds_dwordx4 v146, s[100:101]
	s_nop 0
	s_nop 0
	s_nop 0
	s_nop 0
	s_nop 0
	s_waitcnt vmcnt(8) lgkmcnt(0)
	s_barrier
	s_setprio 0
	s_waitcnt lgkmcnt(0)
	v_mfma_f32_16x16x32_bf16 v[66:69], v[134:137], v[216:219], v[66:69]
	v_mfma_f32_16x16x32_bf16 v[62:65], v[154:157], v[216:219], v[62:65]
	v_mfma_f32_16x16x32_bf16 v[58:61], v[134:137], v[224:227], v[58:61]
	v_mfma_f32_16x16x32_bf16 v[54:57], v[154:157], v[224:227], v[54:57]
	v_mfma_f32_16x16x32_bf16 v[50:53], v[134:137], v[232:235], v[50:53]
	v_mfma_f32_16x16x32_bf16 v[46:49], v[154:157], v[232:235], v[46:49]
	v_mfma_f32_16x16x32_bf16 v[42:45], v[134:137], v[240:243], v[42:45]
	v_mfma_f32_16x16x32_bf16 v[38:41], v[154:157], v[240:243], v[38:41]
	v_mfma_f32_16x16x32_bf16 v[66:69], v[138:141], v[220:223], v[66:69]
	v_mfma_f32_16x16x32_bf16 v[62:65], v[158:161], v[220:223], v[62:65]
	v_mfma_f32_16x16x32_bf16 v[58:61], v[138:141], v[228:231], v[58:61]
	v_mfma_f32_16x16x32_bf16 v[54:57], v[158:161], v[228:231], v[54:57]
	v_mfma_f32_16x16x32_bf16 v[50:53], v[138:141], v[236:239], v[50:53]
	v_mfma_f32_16x16x32_bf16 v[46:49], v[158:161], v[236:239], v[46:49]
	v_mfma_f32_16x16x32_bf16 v[42:45], v[138:141], v[244:247], v[42:45]
	v_mfma_f32_16x16x32_bf16 v[38:41], v[158:161], v[244:247], v[38:41]
	v_mfma_f32_16x16x32_bf16 v[34:37], v[178:181], v[216:219], v[34:37]
	ds_read_b128 v[134:137], v175
	v_mfma_f32_16x16x32_bf16 v[30:33], v[208:211], v[216:219], v[30:33]
	ds_read_b128 v[138:141], v175 offset:1024
	v_mfma_f32_16x16x32_bf16 v[26:29], v[178:181], v[224:227], v[26:29]
	ds_read_b128 v[154:157], v175 offset:2048
	v_mfma_f32_16x16x32_bf16 v[22:25], v[208:211], v[224:227], v[22:25]
	s_add_i32 s26, s26, 2
	s_add_u32 s40, s40, 0x100
	s_addc_u32 s41, s41, 0
	s_add_u32 s11, s11, 0x100
	s_addc_u32 s13, s13, 0
	s_add_u32 s27, s40, 0xfffc0080
	s_addc_u32 s29, s41, -1
	s_add_i32 s31, 0, 0x10000
	s_cmp_eq_u32 s26, 12
	s_cselect_b32 s45, s1, s29
	s_cselect_b32 s44, s0, s27
	s_cselect_b32 s43, s35, s13
	s_cselect_b32 s42, s34, s11
	s_add_i32 s27, 0, 0x14000
	ds_read_b128 v[158:161], v175 offset:3072
	v_mfma_f32_16x16x32_bf16 v[18:21], v[178:181], v[232:235], v[18:21]
	v_mfma_f32_16x16x32_bf16 v[14:17], v[208:211], v[232:235], v[14:17]
	v_mfma_f32_16x16x32_bf16 v[8:11], v[178:181], v[240:243], v[10:13]
	v_mfma_f32_16x16x32_bf16 v[4:7], v[208:211], v[240:243], v[4:7]
	v_mfma_f32_16x16x32_bf16 v[34:37], v[204:207], v[220:223], v[34:37]
	v_mfma_f32_16x16x32_bf16 v[30:33], v[212:215], v[220:223], v[30:33]
	v_mfma_f32_16x16x32_bf16 v[26:29], v[204:207], v[228:231], v[26:29]
	v_mfma_f32_16x16x32_bf16 v[22:25], v[212:215], v[228:231], v[22:25]
	v_mfma_f32_16x16x32_bf16 v[18:21], v[204:207], v[236:239], v[18:21]
	v_mfma_f32_16x16x32_bf16 v[14:17], v[212:215], v[236:239], v[14:17]
	v_mfma_f32_16x16x32_bf16 v[10:13], v[204:207], v[244:247], v[8:11]
	v_mfma_f32_16x16x32_bf16 v[6:9], v[212:215], v[244:247], v[4:7]
	s_setprio 3
	s_barrier
	s_cmp_gt_u32 s26, 13
	s_cbranch_scc0 .LBB0_2096
	s_and_b64 vcc, exec, s[8:9]
	s_cbranch_vccz .LBB0_2099
	s_barrier

;     __device__ __forceinline__ bool next(int i, Unit& u) const { if (!StaticOrder::next(i / 3, u)) return false; u.aux = i % 3; return true; }
; #define PG8_STAGE(bufoff, gbase, voff) do { _Pragma("unroll") for (int _i = 0; _i < 2; ++_i) \
;         __builtin_amdgcn_global_load_lds((const unsigned*)((const char*)(gbase) + (voff)[_i]), (PG8_LAS unsigned*)(lds + (bufoff) + ldsw + _i * 8192), 16, 0, 0); } while (0)
; #define PG8_LDA(dst, b, h) do { _Pragma("unroll") for (int m = 0; m < 4; ++m) _Pragma("unroll") for (int k = 0; k < 2; ++k) dst[m][k] = *(const PG8_LAS bf16x8*)(lds + PG8_SA(b, h) + aoff + m * 2048 + k * 1024); } while (0)
; #define PG8_LDB(dst, b, h) do { _Pragma("unroll") for (int n = 0; n < 2; ++n) _Pragma("unroll") for (int k = 0; k < 2; ++k) dst[n][k] = *(const PG8_LAS bf16x8*)(lds + PG8_SB(b, h) + boff + n * 2048 + k * 1024); } while (0)
; #define PG8_WAIT_V(n) asm volatile("s_waitcnt vmcnt(" #n ")" ::: "memory")
; #define PG8_WAIT_L(n) asm volatile("s_waitcnt lgkmcnt(" #n ")" ::: "memory")
; template <class Epi, class Sched, bool ALIGN_EPI = false, bool SP2 = false>
; __device__ __forceinline__ void gemm_phase(PG8_LAS unsigned char* lds, const Gemm g, const Sched& S, const Epi& E) {
;     ...
;         const bool has_next = S.next(ui + 1, nxt);
;         const char* nA = cA; const char* nB = cB; if (has_next) S.bases(g, nxt, tstep, nA, nB);
;         for (int t = 0; t < nt; t += 2) {
;             const bool last = (t == nt - 2);
;             const char* a1 = cA + (size_t)(t + 1) * kstep;
;             const char* a2 = last ? nA : cA + (size_t)(t + 2) * kstep; const char* b2 = last ? nB : cB + (size_t)(t + 2) * kstep;
;             const char* a3 = a2 + kstep; const char* b3 = b2 + kstep;
;             if (last && has_next) S.a_ready(nxt);
;             if constexpr (SP2) {
;             PG8_LDB(B0, 0, 0); PG8_LDB(B1, 0, 1); PG8_SCHED; PG8_LDA(At, 0, 0); PG8_STAGE(PG8_SA(1, 1), a1 + hstep, voffA);
;             PG8_WAIT_V(8); PG8_WAIT_L(0); PG8_BAR; PG8_MMA(0, 0, At, B0); PG8_MMA(0, 1, At, B1); PG8_BAR; PG8_SCHED;
;     ...
;         if (zero_acc) {
; #pragma unroll
;         for (int a = 0; a < 2; ++a)
; #pragma unroll
;             for (int b = 0; b < 2; ++b)
; #pragma unroll
;                 for (int m = 0; m < 4; ++m)
; #pragma unroll
;                     for (int n = 0; n < 2; ++n) acc[a][b][m][n] = (f32x4){0.f, 0.f, 0.f, 0.f};
.LBB0_2184:
	s_add_u32 s2, s42, 0x100
	v_mov_b32_e32 v4, 0
	s_addc_u32 s29, s43, 0
	s_mov_b32 s31, -2
	s_waitcnt lgkmcnt(0)
	v_mov_b32_e32 v5, v4
	v_mov_b32_e32 v6, v4
	v_mov_b32_e32 v7, v4
	v_mov_b32_e32 v8, v4
	v_mov_b32_e32 v9, v4
	v_mov_b32_e32 v10, v4
	v_mov_b32_e32 v11, v4
	v_mov_b32_e32 v20, v4
	v_mov_b32_e32 v21, v4
	v_mov_b32_e32 v22, v4
	v_mov_b32_e32 v23, v4
	v_mov_b32_e32 v24, v4
	v_mov_b32_e32 v25, v4
	v_mov_b32_e32 v26, v4
	v_mov_b32_e32 v27, v4
	v_mov_b32_e32 v36, v4
	v_mov_b32_e32 v37, v4
	v_mov_b32_e32 v38, v4
	v_mov_b32_e32 v39, v4
	v_mov_b32_e32 v40, v4
	v_mov_b32_e32 v41, v4
	v_mov_b32_e32 v42, v4
	v_mov_b32_e32 v43, v4
	v_mov_b32_e32 v52, v4
	v_mov_b32_e32 v53, v4
	v_mov_b32_e32 v54, v4
	v_mov_b32_e32 v55, v4
	v_mov_b32_e32 v56, v4
	v_mov_b32_e32 v57, v4
	v_mov_b32_e32 v58, v4
	v_mov_b32_e32 v59, v4
	v_mov_b32_e32 v12, v4
	v_mov_b32_e32 v13, v4
	v_mov_b32_e32 v14, v4
	v_mov_b32_e32 v15, v4
	v_mov_b32_e32 v16, v4
	v_mov_b32_e32 v17, v4
	v_mov_b32_e32 v18, v4
	v_mov_b32_e32 v19, v4
	v_mov_b32_e32 v28, v4
	v_mov_b32_e32 v29, v4
	v_mov_b32_e32 v30, v4
	v_mov_b32_e32 v31, v4
	v_mov_b32_e32 v32, v4
	v_mov_b32_e32 v33, v4
	v_mov_b32_e32 v34, v4
	v_mov_b32_e32 v35, v4
	v_mov_b32_e32 v44, v4
	v_mov_b32_e32 v45, v4
	v_mov_b32_e32 v46, v4
	v_mov_b32_e32 v47, v4
	v_mov_b32_e32 v48, v4
	v_mov_b32_e32 v49, v4
	v_mov_b32_e32 v50, v4
	v_mov_b32_e32 v51, v4
	v_mov_b32_e32 v60, v4
	v_mov_b32_e32 v61, v4
	v_mov_b32_e32 v62, v4
	v_mov_b32_e32 v63, v4
	v_mov_b32_e32 v64, v4
	v_mov_b32_e32 v65, v4
	v_mov_b32_e32 v66, v4
	v_mov_b32_e32 v67, v4
	v_mov_b32_e32 v68, v4
	v_mov_b32_e32 v69, v4
	v_mov_b32_e32 v70, v4
	v_mov_b32_e32 v71, v4
	v_mov_b32_e32 v72, v4
	v_mov_b32_e32 v73, v4
	v_mov_b32_e32 v74, v4
	v_mov_b32_e32 v75, v4
	v_mov_b32_e32 v84, v4
	v_mov_b32_e32 v85, v4
	v_mov_b32_e32 v86, v4
	v_mov_b32_e32 v87, v4
	v_mov_b32_e32 v88, v4
	v_mov_b32_e32 v89, v4
	v_mov_b32_e32 v90, v4
	v_mov_b32_e32 v91, v4
	v_mov_b32_e32 v100, v4
	v_mov_b32_e32 v101, v4
	v_mov_b32_e32 v102, v4
	v_mov_b32_e32 v103, v4
	v_mov_b32_e32 v104, v4
	v_mov_b32_e32 v105, v4
	v_mov_b32_e32 v106, v4
	v_mov_b32_e32 v107, v4
	v_mov_b32_e32 v116, v4
	v_mov_b32_e32 v117, v4
	v_mov_b32_e32 v118, v4
	v_mov_b32_e32 v119, v4
	v_mov_b32_e32 v120, v4
	v_mov_b32_e32 v121, v4
	v_mov_b32_e32 v122, v4
	v_mov_b32_e32 v123, v4
	v_mov_b32_e32 v76, v4
	v_mov_b32_e32 v77, v4
	v_mov_b32_e32 v78, v4
	v_mov_b32_e32 v79, v4
	v_mov_b32_e32 v80, v4
	v_mov_b32_e32 v81, v4
	v_mov_b32_e32 v82, v4
	v_mov_b32_e32 v83, v4
	v_mov_b32_e32 v92, v4
	v_mov_b32_e32 v93, v4
	v_mov_b32_e32 v94, v4
	v_mov_b32_e32 v95, v4
	v_mov_b32_e32 v96, v4
	v_mov_b32_e32 v97, v4
	v_mov_b32_e32 v98, v4
	v_mov_b32_e32 v99, v4
	v_mov_b32_e32 v108, v4
	v_mov_b32_e32 v109, v4
	v_mov_b32_e32 v110, v4
	v_mov_b32_e32 v111, v4
	v_mov_b32_e32 v112, v4
	v_mov_b32_e32 v113, v4
	v_mov_b32_e32 v114, v4
	v_mov_b32_e32 v115, v4
	v_mov_b32_e32 v124, v4
	v_mov_b32_e32 v125, v4
	v_mov_b32_e32 v126, v4
	v_mov_b32_e32 v127, v4
	v_mov_b32_e32 v128, v4
	v_mov_b32_e32 v129, v4
	v_mov_b32_e32 v130, v4
	v_mov_b32_e32 v131, v4
	v_add_u32_e32 v243, 0x10000, v173
	ds_read_b128 v[142:145], v243
	ds_read_b128 v[146:149], v243 offset:1024
	ds_read_b128 v[150:153], v243 offset:2048
	ds_read_b128 v[154:157], v243 offset:3072
	s_add_u32 s42, s40, 0x100
	s_addc_u32 s43, s41, 0
	s_add_i32 s37, 0, 0x10000
	s_cmp_eq_u32 s31, 28
	s_cselect_b32 s47, s5, s43
	s_cselect_b32 s46, s4, s42
	s_cselect_b32 s45, s35, s29
	s_cselect_b32 s44, s34, s2
	s_add_i32 s39, 0, 0x14000
	.p2align 6
	s_nop 0
.LBB0_2185:
	ds_read_b128 v[158:161], v243 offset:16384
	ds_read_b128 v[174:177], v243 offset:17408
	ds_read_b128 v[180:183], v243 offset:18432
	ds_read_b128 v[204:207], v243 offset:19456
	v_lshl_add_u64 v[162:163], s[40:41], 0, v[138:139]
	s_add_i32 m0, s55, 0xc000
	ds_read_b128 v[208:211], v179
	ds_read_b128 v[212:215], v179 offset:1024
	ds_read_b128 v[216:219], v179 offset:2048
	ds_read_b128 v[220:223], v179 offset:3072
	ds_read_b128 v[224:227], v179 offset:4096
	ds_read_b128 v[228:231], v179 offset:5120
	ds_read_b128 v[232:235], v179 offset:6144
	ds_read_b128 v[236:239], v179 offset:7168
	global_load_lds_dwordx4 v[162:163], off
	v_lshl_add_u64 v[162:163], s[40:41], 0, v[140:141]
	s_add_i32 m0, s55, 0xe000
	s_nop 0
	global_load_lds_dwordx4 v[162:163], off
	s_nop 0
	s_waitcnt vmcnt(8) lgkmcnt(0)
	s_barrier
	s_setprio 0
	s_waitcnt lgkmcnt(0)
	v_mfma_f32_16x16x32_bf16 v[128:131], v[142:145], v[208:211], v[128:131]
	v_mfma_f32_16x16x32_bf16 v[124:127], v[150:153], v[208:211], v[124:127]
	v_mfma_f32_16x16x32_bf16 v[112:115], v[142:145], v[216:219], v[112:115]
	v_mfma_f32_16x16x32_bf16 v[108:111], v[150:153], v[216:219], v[108:111]
	v_mfma_f32_16x16x32_bf16 v[96:99], v[142:145], v[224:227], v[96:99]
	v_mfma_f32_16x16x32_bf16 v[92:95], v[150:153], v[224:227], v[92:95]
	v_mfma_f32_16x16x32_bf16 v[80:83], v[142:145], v[232:235], v[80:83]
	v_mfma_f32_16x16x32_bf16 v[76:79], v[150:153], v[232:235], v[76:79]
	v_mfma_f32_16x16x32_bf16 v[128:131], v[146:149], v[212:215], v[128:131]
	v_mfma_f32_16x16x32_bf16 v[124:127], v[154:157], v[212:215], v[124:127]
	v_mfma_f32_16x16x32_bf16 v[112:115], v[146:149], v[220:223], v[112:115]
	v_mfma_f32_16x16x32_bf16 v[108:111], v[154:157], v[220:223], v[108:111]
	v_mfma_f32_16x16x32_bf16 v[96:99], v[146:149], v[228:231], v[96:99]
	v_mfma_f32_16x16x32_bf16 v[92:95], v[154:157], v[228:231], v[92:95]
	v_mfma_f32_16x16x32_bf16 v[80:83], v[146:149], v[236:239], v[80:83]
	v_mfma_f32_16x16x32_bf16 v[76:79], v[154:157], v[236:239], v[76:79]
	v_mfma_f32_16x16x32_bf16 v[120:123], v[158:161], v[208:211], v[120:123]
	v_mfma_f32_16x16x32_bf16 v[116:119], v[180:183], v[208:211], v[116:119]
	v_mfma_f32_16x16x32_bf16 v[104:107], v[158:161], v[216:219], v[104:107]
	v_mfma_f32_16x16x32_bf16 v[100:103], v[180:183], v[216:219], v[100:103]
	v_mfma_f32_16x16x32_bf16 v[88:91], v[158:161], v[224:227], v[88:91]
	v_mfma_f32_16x16x32_bf16 v[84:87], v[180:183], v[224:227], v[84:87]
	v_mfma_f32_16x16x32_bf16 v[72:75], v[158:161], v[232:235], v[72:75]
	v_mfma_f32_16x16x32_bf16 v[68:71], v[180:183], v[232:235], v[68:71]
	v_mfma_f32_16x16x32_bf16 v[120:123], v[174:177], v[212:215], v[120:123]
	v_mfma_f32_16x16x32_bf16 v[116:119], v[204:207], v[212:215], v[116:119]
	v_mfma_f32_16x16x32_bf16 v[104:107], v[174:177], v[220:223], v[104:107]
	v_mfma_f32_16x16x32_bf16 v[100:103], v[204:207], v[220:223], v[100:103]
	v_mfma_f32_16x16x32_bf16 v[88:91], v[174:177], v[228:231], v[88:91]
	v_mfma_f32_16x16x32_bf16 v[84:87], v[204:207], v[228:231], v[84:87]
	v_mfma_f32_16x16x32_bf16 v[72:75], v[174:177], v[236:239], v[72:75]
	v_mfma_f32_16x16x32_bf16 v[68:71], v[204:207], v[236:239], v[68:71]
	s_setprio 3
	s_barrier
; #define PG8_STAGE(bufoff, gbase, voff) do { _Pragma("unroll") for (int _i = 0; _i < 2; ++_i) \
;         __builtin_amdgcn_global_load_lds((const unsigned*)((const char*)(gbase) + (voff)[_i]), (PG8_LAS unsigned*)(lds + (bufoff) + ldsw + _i * 8192), 16, 0, 0); } while (0)
; #define PG8_LDA(dst, b, h) do { _Pragma("unroll") for (int m = 0; m < 4; ++m) _Pragma("unroll") for (int k = 0; k < 2; ++k) dst[m][k] = *(const PG8_LAS bf16x8*)(lds + PG8_SA(b, h) + aoff + m * 2048 + k * 1024); } while (0)
; #define PG8_LDB(dst, b, h) do { _Pragma("unroll") for (int n = 0; n < 2; ++n) _Pragma("unroll") for (int k = 0; k < 2; ++k) dst[n][k] = *(const PG8_LAS bf16x8*)(lds + PG8_SB(b, h) + boff + n * 2048 + k * 1024); } while (0)
; #define PG8_MMA(ai, bj, At, Bt) do { __builtin_amdgcn_s_setprio(1); _Pragma("unroll") for (int m = 0; m < 4; ++m) _Pragma("unroll") for (int n = 0; n < 2; ++n) _Pragma("unroll") for (int k = 0; k < 2; ++k) \
;         acc[ai][bj][m][n] = __builtin_amdgcn_mfma_f32_16x16x32_bf16(Bt[n][k], At[m][k], acc[ai][bj][m][n], 0, 0, 0); __builtin_amdgcn_s_setprio(0); } while (0)
; #define PG8_WAIT_V(n) asm volatile("s_waitcnt vmcnt(" #n ")" ::: "memory")
; #define PG8_WAIT_L(n) asm volatile("s_waitcnt lgkmcnt(" #n ")" ::: "memory")
; #define PG8_BAR __builtin_amdgcn_s_barrier()
; #define PG8_SCHED __builtin_amdgcn_sched_barrier(0)
; template <class Epi, class Sched, bool ALIGN_EPI = false, bool SP2 = false>
; __device__ __forceinline__ void gemm_phase(PG8_LAS unsigned char* lds, const Gemm g, const Sched& S, const Epi& E) {
;     ...
;             PG8_LDA(At, 0, 1); PG8_STAGE(PG8_SB(0, 0), b2, voffB); PG8_STAGE(PG8_SB(0, 1), b2 + hstep, voffB); PG8_STAGE(PG8_SA(0, 0), a2, voffA);
;             PG8_WAIT_V(8); PG8_WAIT_L(0); PG8_BAR; PG8_MMA(1, 0, At, B0); PG8_MMA(1, 1, At, B1); PG8_BAR; PG8_SCHED;
;             PG8_LDB(B0, 1, 0); PG8_LDB(B1, 1, 1); PG8_SCHED; PG8_LDA(At, 1, 0); PG8_STAGE(PG8_SA(0, 1), a2 + hstep, voffA);
	s_add_i32 s37, s37, s54
	s_mov_b32 m0, s37
	ds_read_b128 v[208:211], v179 offset:16384
	ds_read_b128 v[212:215], v179 offset:17408
	ds_read_b128 v[216:219], v179 offset:18432
	ds_read_b128 v[220:223], v179 offset:19456
	ds_read_b128 v[224:227], v179 offset:20480
	ds_read_b128 v[228:231], v179 offset:21504
	ds_read_b128 v[232:235], v179 offset:22528
	ds_read_b128 v[236:239], v179 offset:23552
	global_load_lds_dwordx4 v2, s[44:45]
	s_add_i32 m0, s37, 0x2000
	s_add_u32 s40, s44, 0x80000
	s_addc_u32 s41, s45, 0
	s_add_i32 s37, s39, s54
	global_load_lds_dwordx4 v132, s[44:45]
	s_mov_b32 m0, s37
	s_nop 0
	global_load_lds_dwordx4 v2, s[40:41]
	s_add_i32 m0, s37, 0x2000
	s_nop 0
	global_load_lds_dwordx4 v132, s[40:41]
	s_mov_b32 m0, s55
	s_nop 0
	global_load_lds_dwordx4 v2, s[46:47]
	s_mov_b32 m0, s56
	s_nop 0
	global_load_lds_dwordx4 v132, s[46:47]
	s_nop 0
	s_waitcnt vmcnt(8) lgkmcnt(0)
	s_barrier
	s_setprio 0
	s_waitcnt lgkmcnt(0)
	v_mfma_f32_16x16x32_bf16 v[64:67], v[142:145], v[208:211], v[64:67]
	v_mfma_f32_16x16x32_bf16 v[60:63], v[150:153], v[208:211], v[60:63]
	v_mfma_f32_16x16x32_bf16 v[48:51], v[142:145], v[216:219], v[48:51]
	v_mfma_f32_16x16x32_bf16 v[44:47], v[150:153], v[216:219], v[44:47]
	v_mfma_f32_16x16x32_bf16 v[32:35], v[142:145], v[224:227], v[32:35]
	v_mfma_f32_16x16x32_bf16 v[28:31], v[150:153], v[224:227], v[28:31]
	v_mfma_f32_16x16x32_bf16 v[16:19], v[142:145], v[232:235], v[16:19]
	v_mfma_f32_16x16x32_bf16 v[12:15], v[150:153], v[232:235], v[12:15]
	v_mfma_f32_16x16x32_bf16 v[64:67], v[146:149], v[212:215], v[64:67]
	v_mfma_f32_16x16x32_bf16 v[60:63], v[154:157], v[212:215], v[60:63]
	v_mfma_f32_16x16x32_bf16 v[48:51], v[146:149], v[220:223], v[48:51]
	v_mfma_f32_16x16x32_bf16 v[44:47], v[154:157], v[220:223], v[44:47]
	v_mfma_f32_16x16x32_bf16 v[32:35], v[146:149], v[228:231], v[32:35]
	v_mfma_f32_16x16x32_bf16 v[28:31], v[154:157], v[228:231], v[28:31]
	v_mfma_f32_16x16x32_bf16 v[16:19], v[146:149], v[236:239], v[16:19]
	v_mfma_f32_16x16x32_bf16 v[12:15], v[154:157], v[236:239], v[12:15]
	v_mfma_f32_16x16x32_bf16 v[56:59], v[158:161], v[208:211], v[56:59]
	ds_read_b128 v[142:145], v243 offset:32768
	v_mfma_f32_16x16x32_bf16 v[52:55], v[180:183], v[208:211], v[52:55]
	ds_read_b128 v[146:149], v243 offset:33792
	v_mfma_f32_16x16x32_bf16 v[40:43], v[158:161], v[216:219], v[40:43]
	ds_read_b128 v[150:153], v243 offset:34816
	v_mfma_f32_16x16x32_bf16 v[36:39], v[180:183], v[216:219], v[36:39]
	ds_read_b128 v[154:157], v243 offset:35840
	v_mfma_f32_16x16x32_bf16 v[24:27], v[158:161], v[224:227], v[24:27]
	v_mfma_f32_16x16x32_bf16 v[20:23], v[180:183], v[224:227], v[20:23]
	v_mfma_f32_16x16x32_bf16 v[8:11], v[158:161], v[232:235], v[8:11]
	v_mfma_f32_16x16x32_bf16 v[4:7], v[180:183], v[232:235], v[4:7]
	v_mfma_f32_16x16x32_bf16 v[56:59], v[174:177], v[212:215], v[56:59]
	v_mfma_f32_16x16x32_bf16 v[52:55], v[204:207], v[212:215], v[52:55]
	v_mfma_f32_16x16x32_bf16 v[40:43], v[174:177], v[220:223], v[40:43]
	v_mfma_f32_16x16x32_bf16 v[36:39], v[204:207], v[220:223], v[36:39]
	v_mfma_f32_16x16x32_bf16 v[24:27], v[174:177], v[228:231], v[24:27]
	v_mfma_f32_16x16x32_bf16 v[20:23], v[204:207], v[228:231], v[20:23]
	v_mfma_f32_16x16x32_bf16 v[8:11], v[174:177], v[236:239], v[8:11]
	v_mfma_f32_16x16x32_bf16 v[4:7], v[204:207], v[236:239], v[4:7]
	s_setprio 3
	s_barrier
	s_add_i32 s37, 0, 0x18000
	s_add_i32 s39, 0, 0x1c000
	ds_read_b128 v[158:161], v243 offset:49152
	ds_read_b128 v[174:177], v243 offset:50176
	ds_read_b128 v[180:183], v243 offset:51200
	ds_read_b128 v[204:207], v243 offset:52224
	s_add_u32 s40, s46, 0x80000
	s_addc_u32 s41, s47, 0
	s_mov_b32 m0, s57
	ds_read_b128 v[208:211], v179 offset:32768
	ds_read_b128 v[212:215], v179 offset:33792
	ds_read_b128 v[216:219], v179 offset:34816
	ds_read_b128 v[220:223], v179 offset:35840
	ds_read_b128 v[224:227], v179 offset:36864
	ds_read_b128 v[228:231], v179 offset:37888
	ds_read_b128 v[232:235], v179 offset:38912
	ds_read_b128 v[236:239], v179 offset:39936
	global_load_lds_dwordx4 v2, s[40:41]
	s_mov_b32 m0, s58
	s_nop 0
	global_load_lds_dwordx4 v132, s[40:41]
	s_waitcnt vmcnt(8) lgkmcnt(0)
	s_barrier
; #define PG8_STAGE(bufoff, gbase, voff) do { _Pragma("unroll") for (int _i = 0; _i < 2; ++_i) \
;         __builtin_amdgcn_global_load_lds((const unsigned*)((const char*)(gbase) + (voff)[_i]), (PG8_LAS unsigned*)(lds + (bufoff) + ldsw + _i * 8192), 16, 0, 0); } while (0)
; #define PG8_LDA(dst, b, h) do { _Pragma("unroll") for (int m = 0; m < 4; ++m) _Pragma("unroll") for (int k = 0; k < 2; ++k) dst[m][k] = *(const PG8_LAS bf16x8*)(lds + PG8_SA(b, h) + aoff + m * 2048 + k * 1024); } while (0)
; #define PG8_LDB(dst, b, h) do { _Pragma("unroll") for (int n = 0; n < 2; ++n) _Pragma("unroll") for (int k = 0; k < 2; ++k) dst[n][k] = *(const PG8_LAS bf16x8*)(lds + PG8_SB(b, h) + boff + n * 2048 + k * 1024); } while (0)
; #define PG8_MMA(ai, bj, At, Bt) do { __builtin_amdgcn_s_setprio(1); _Pragma("unroll") for (int m = 0; m < 4; ++m) _Pragma("unroll") for (int n = 0; n < 2; ++n) _Pragma("unroll") for (int k = 0; k < 2; ++k) \
;         acc[ai][bj][m][n] = __builtin_amdgcn_mfma_f32_16x16x32_bf16(Bt[n][k], At[m][k], acc[ai][bj][m][n], 0, 0, 0); __builtin_amdgcn_s_setprio(0); } while (0)
; #define PG8_WAIT_V(n) asm volatile("s_waitcnt vmcnt(" #n ")" ::: "memory")
; #define PG8_WAIT_L(n) asm volatile("s_waitcnt lgkmcnt(" #n ")" ::: "memory")
; template <class Epi, class Sched, bool ALIGN_EPI = false, bool SP2 = false>
; __device__ __forceinline__ void gemm_phase(PG8_LAS unsigned char* lds, const Gemm g, const Sched& S, const Epi& E) {
;     ...
;         for (int t = 0; t < nt; t += 2) {
;             const bool last = (t == nt - 2);
;             const char* a1 = cA + (size_t)(t + 1) * kstep;
;             const char* a2 = last ? nA : cA + (size_t)(t + 2) * kstep; const char* b2 = last ? nB : cB + (size_t)(t + 2) * kstep;
;             const char* a3 = a2 + kstep; const char* b3 = b2 + kstep;
;             if (last && has_next) S.a_ready(nxt);
;     ...
;             PG8_LDB(B0, 1, 0); PG8_LDB(B1, 1, 1); PG8_SCHED; PG8_LDA(At, 1, 0); PG8_STAGE(PG8_SA(0, 1), a2 + hstep, voffA);
;             PG8_WAIT_V(8); PG8_WAIT_L(0); PG8_BAR; PG8_MMA(0, 0, At, B0); PG8_MMA(0, 1, At, B1); PG8_BAR; PG8_SCHED;
;             PG8_LDA(At, 1, 1); PG8_STAGE(PG8_SB(1, 0), b3, voffB); PG8_STAGE(PG8_SB(1, 1), b3 + hstep, voffB); PG8_STAGE(PG8_SA(1, 0), a3, voffA);
;             PG8_WAIT_V(8); PG8_WAIT_L(0); PG8_BAR; PG8_MMA(1, 0, At, B0); PG8_MMA(1, 1, At, B1); PG8_BAR; PG8_SCHED;
	s_setprio 0
	s_waitcnt lgkmcnt(0)
	v_mfma_f32_16x16x32_bf16 v[128:131], v[142:145], v[208:211], v[128:131]
	v_mfma_f32_16x16x32_bf16 v[124:127], v[150:153], v[208:211], v[124:127]
	v_mfma_f32_16x16x32_bf16 v[112:115], v[142:145], v[216:219], v[112:115]
	v_mfma_f32_16x16x32_bf16 v[108:111], v[150:153], v[216:219], v[108:111]
	v_mfma_f32_16x16x32_bf16 v[96:99], v[142:145], v[224:227], v[96:99]
	v_mfma_f32_16x16x32_bf16 v[92:95], v[150:153], v[224:227], v[92:95]
	v_mfma_f32_16x16x32_bf16 v[80:83], v[142:145], v[232:235], v[80:83]
	v_mfma_f32_16x16x32_bf16 v[76:79], v[150:153], v[232:235], v[76:79]
	v_mfma_f32_16x16x32_bf16 v[128:131], v[146:149], v[212:215], v[128:131]
	v_mfma_f32_16x16x32_bf16 v[124:127], v[154:157], v[212:215], v[124:127]
	v_mfma_f32_16x16x32_bf16 v[112:115], v[146:149], v[220:223], v[112:115]
	v_mfma_f32_16x16x32_bf16 v[108:111], v[154:157], v[220:223], v[108:111]
	v_mfma_f32_16x16x32_bf16 v[96:99], v[146:149], v[228:231], v[96:99]
	v_mfma_f32_16x16x32_bf16 v[92:95], v[154:157], v[228:231], v[92:95]
	v_mfma_f32_16x16x32_bf16 v[80:83], v[146:149], v[236:239], v[80:83]
	v_mfma_f32_16x16x32_bf16 v[76:79], v[154:157], v[236:239], v[76:79]
	v_mfma_f32_16x16x32_bf16 v[120:123], v[158:161], v[208:211], v[120:123]
	v_mfma_f32_16x16x32_bf16 v[116:119], v[180:183], v[208:211], v[116:119]
	v_mfma_f32_16x16x32_bf16 v[104:107], v[158:161], v[216:219], v[104:107]
	v_mfma_f32_16x16x32_bf16 v[100:103], v[180:183], v[216:219], v[100:103]
	v_mfma_f32_16x16x32_bf16 v[88:91], v[158:161], v[224:227], v[88:91]
	v_mfma_f32_16x16x32_bf16 v[84:87], v[180:183], v[224:227], v[84:87]
	v_mfma_f32_16x16x32_bf16 v[72:75], v[158:161], v[232:235], v[72:75]
	v_mfma_f32_16x16x32_bf16 v[68:71], v[180:183], v[232:235], v[68:71]
	v_mfma_f32_16x16x32_bf16 v[120:123], v[174:177], v[212:215], v[120:123]
	v_mfma_f32_16x16x32_bf16 v[116:119], v[204:207], v[212:215], v[116:119]
	v_mfma_f32_16x16x32_bf16 v[104:107], v[174:177], v[220:223], v[104:107]
	v_mfma_f32_16x16x32_bf16 v[100:103], v[204:207], v[220:223], v[100:103]
	v_mfma_f32_16x16x32_bf16 v[88:91], v[174:177], v[228:231], v[88:91]
	v_mfma_f32_16x16x32_bf16 v[84:87], v[204:207], v[228:231], v[84:87]
	v_mfma_f32_16x16x32_bf16 v[72:75], v[174:177], v[236:239], v[72:75]
	v_mfma_f32_16x16x32_bf16 v[68:71], v[204:207], v[236:239], v[68:71]
	s_setprio 3
	s_barrier
	s_add_i32 s37, s37, s54
	s_add_i32 m0, s37, 0xffffff80
	ds_read_b128 v[208:211], v179 offset:49152
	ds_read_b128 v[212:215], v179 offset:50176
	ds_read_b128 v[216:219], v179 offset:51200
	ds_read_b128 v[220:223], v179 offset:52224
	ds_read_b128 v[224:227], v179 offset:53248
	ds_read_b128 v[228:231], v179 offset:54272
	ds_read_b128 v[232:235], v179 offset:55296
	ds_read_b128 v[236:239], v179 offset:56320
	global_load_lds_dwordx4 v2, s[44:45] offset:128
	s_add_i32 m0, s37, 0x1f80
	s_add_u32 s40, s44, 0x80080
	s_addc_u32 s41, s45, 0
	s_add_i32 s37, s39, s54
	global_load_lds_dwordx4 v132, s[44:45] offset:128
	s_mov_b32 m0, s37
	s_nop 0
	global_load_lds_dwordx4 v2, s[40:41]
	s_add_i32 m0, s37, 0x2000
	s_nop 0
	global_load_lds_dwordx4 v132, s[40:41]
	s_add_i32 m0, s60, 0xffffff80
	s_nop 0
	global_load_lds_dwordx4 v2, s[46:47] offset:128
	s_add_i32 m0, s61, 0xffffff80
	s_nop 0
	global_load_lds_dwordx4 v132, s[46:47] offset:128
	s_nop 0
	s_nop 0
	s_nop 0
	s_nop 0
	s_nop 0
	s_nop 0
	s_waitcnt vmcnt(8) lgkmcnt(0)
	s_barrier
	s_setprio 0
	s_waitcnt lgkmcnt(0)
	v_mfma_f32_16x16x32_bf16 v[64:67], v[142:145], v[208:211], v[64:67]
	v_mfma_f32_16x16x32_bf16 v[60:63], v[150:153], v[208:211], v[60:63]
	v_mfma_f32_16x16x32_bf16 v[48:51], v[142:145], v[216:219], v[48:51]
	v_mfma_f32_16x16x32_bf16 v[44:47], v[150:153], v[216:219], v[44:47]
	v_mfma_f32_16x16x32_bf16 v[32:35], v[142:145], v[224:227], v[32:35]
	v_mfma_f32_16x16x32_bf16 v[28:31], v[150:153], v[224:227], v[28:31]
	v_mfma_f32_16x16x32_bf16 v[16:19], v[142:145], v[232:235], v[16:19]
	v_mfma_f32_16x16x32_bf16 v[12:15], v[150:153], v[232:235], v[12:15]
	v_mfma_f32_16x16x32_bf16 v[64:67], v[146:149], v[212:215], v[64:67]
	v_mfma_f32_16x16x32_bf16 v[60:63], v[154:157], v[212:215], v[60:63]
	v_mfma_f32_16x16x32_bf16 v[48:51], v[146:149], v[220:223], v[48:51]
	v_mfma_f32_16x16x32_bf16 v[44:47], v[154:157], v[220:223], v[44:47]
	v_mfma_f32_16x16x32_bf16 v[32:35], v[146:149], v[228:231], v[32:35]
	v_mfma_f32_16x16x32_bf16 v[28:31], v[154:157], v[228:231], v[28:31]
	v_mfma_f32_16x16x32_bf16 v[16:19], v[146:149], v[236:239], v[16:19]
	v_mfma_f32_16x16x32_bf16 v[12:15], v[154:157], v[236:239], v[12:15]
	v_mfma_f32_16x16x32_bf16 v[56:59], v[158:161], v[208:211], v[56:59]
	ds_read_b128 v[142:145], v243
	v_mfma_f32_16x16x32_bf16 v[52:55], v[180:183], v[208:211], v[52:55]
	ds_read_b128 v[146:149], v243 offset:1024
	v_mfma_f32_16x16x32_bf16 v[40:43], v[158:161], v[216:219], v[40:43]
	ds_read_b128 v[150:153], v243 offset:2048
	v_mfma_f32_16x16x32_bf16 v[36:39], v[180:183], v[216:219], v[36:39]
	s_add_i32 s31, s31, 2
	s_add_u32 s2, s2, 0x100
	s_addc_u32 s29, s29, 0
	s_mov_b64 s[40:41], s[42:43]
	s_add_u32 s42, s40, 0x100
	s_addc_u32 s43, s41, 0
	s_add_i32 s37, 0, 0x10000
	s_cmp_eq_u32 s31, 28
	s_cselect_b32 s47, s5, s43
	s_cselect_b32 s46, s4, s42
	s_cselect_b32 s45, s35, s29
	s_cselect_b32 s44, s34, s2
	s_add_i32 s39, 0, 0x14000
	ds_read_b128 v[154:157], v243 offset:3072
	v_mfma_f32_16x16x32_bf16 v[24:27], v[158:161], v[224:227], v[24:27]
	v_mfma_f32_16x16x32_bf16 v[20:23], v[180:183], v[224:227], v[20:23]
	v_mfma_f32_16x16x32_bf16 v[8:11], v[158:161], v[232:235], v[8:11]
	v_mfma_f32_16x16x32_bf16 v[4:7], v[180:183], v[232:235], v[4:7]
	v_mfma_f32_16x16x32_bf16 v[56:59], v[174:177], v[212:215], v[56:59]
	v_mfma_f32_16x16x32_bf16 v[52:55], v[204:207], v[212:215], v[52:55]
	v_mfma_f32_16x16x32_bf16 v[40:43], v[174:177], v[220:223], v[40:43]
	v_mfma_f32_16x16x32_bf16 v[36:39], v[204:207], v[220:223], v[36:39]
	v_mfma_f32_16x16x32_bf16 v[24:27], v[174:177], v[228:231], v[24:27]
	v_mfma_f32_16x16x32_bf16 v[20:23], v[204:207], v[228:231], v[20:23]
	v_mfma_f32_16x16x32_bf16 v[8:11], v[174:177], v[236:239], v[8:11]
	v_mfma_f32_16x16x32_bf16 v[4:7], v[204:207], v[236:239], v[4:7]
	s_setprio 3
	s_barrier
	s_cmp_gt_u32 s31, 29
	s_cbranch_scc0 .LBB0_2185
	s_and_b64 vcc, exec, s[26:27]
	s_cbranch_vccz .LBB0_2188
	s_barrier
